# chain2 MFMA order + P5 gate prefetch + P2 slice gain-load batching + P10 epilogue scale prefetch at K-loop start
# speedup vs baseline: 1.0113x; 1.0113x over previous
; #define LAS __attribute__((address_space(3)))
; #define LDS_WAIT() asm volatile("s_waitcnt lgkmcnt(0)" ::: "memory")
; __device__ __forceinline__ void p0_load(const P0Item& it, f32x4 (&w)[16], int lane) {
;     const unsigned voff = (unsigned)(((lane >> 4) * it.ldw + (lane & 15) * 4) * 4);
; #pragma unroll
;     for (int i = 0; i < 16; ++i) w[i] = __builtin_nontemporal_load((const f32x4*)((const char*)(it.src + (size_t)(4 * i) * it.ldw) + voff));
; }
; __device__ __forceinline__ void p0_finish(const P0Item& it, const f32x4 (&w)[16], LAS float* scr, int lane) {
;     const int c4 = (lane & 15) * 4, kr = lane >> 4;
;     if (it.gain) { const unsigned goff = (unsigned)(kr * 4);
; #pragma unroll
;         for (int i = 0; i < 16; ++i) { const float g = *(const float*)((const char*)(it.gain + 4 * i) + goff); *(LAS f32x4*)(scr + (kr + 4 * i) * 68 + c4) = w[i] * g; } }
;     else {
; #pragma unroll
;         for (int i = 0; i < 16; ++i) *(LAS f32x4*)(scr + (kr + 4 * i) * 68 + c4) = w[i]; }
;     LDS_WAIT(); asm volatile("" ::: "memory");
.LBB0_148:
	s_add_i32 s8, s41, 0xfffff800
	s_ashr_i32 s9, s8, 31
	s_lshr_b32 s9, s9, 24
	s_add_i32 s9, s8, s9
	s_ashr_i32 s10, s9, 8
	s_and_b32 s9, s9, 0x3ffff00
	s_sub_i32 s9, s8, s9
	s_lshl_b32 s8, s10, 6
	s_lshl_b32 s10, s9, 6
	s_ashr_i32 s9, s8, 31
	s_lshl_b64 s[12:13], s[8:9], 16
	v_lshl_add_u64 v[66:67], v[138:139], 0, s[12:13]
	s_ashr_i32 s11, s10, 31
	v_lshl_add_u64 v[66:67], s[10:11], 2, v[66:67]
	v_lshl_add_u64 v[66:67], v[66:67], 0, v[140:141]
	v_add_co_u32_e32 v68, vcc, s27, v66
	s_nop 1
	v_addc_co_u32_e32 v69, vcc, 0, v67, vcc
	flat_load_dwordx4 v[126:129], v[66:67] nt
	flat_load_dwordx4 v[122:125], v[68:69] nt
	v_add_co_u32_e32 v68, vcc, s28, v66
	s_nop 1
	v_addc_co_u32_e32 v69, vcc, 0, v67, vcc
	v_add_co_u32_e32 v70, vcc, s29, v66
	s_nop 1
	v_addc_co_u32_e32 v71, vcc, 0, v67, vcc
	flat_load_dwordx4 v[118:121], v[68:69] nt
	flat_load_dwordx4 v[114:117], v[70:71] nt
	v_add_co_u32_e32 v68, vcc, s30, v66
	s_nop 1
	v_addc_co_u32_e32 v69, vcc, 0, v67, vcc
	v_add_co_u32_e32 v70, vcc, s31, v66
	s_nop 1
	v_addc_co_u32_e32 v71, vcc, 0, v67, vcc
	flat_load_dwordx4 v[110:113], v[68:69] nt
	flat_load_dwordx4 v[106:109], v[70:71] nt
	v_add_co_u32_e32 v68, vcc, s34, v66
	s_nop 1
	v_addc_co_u32_e32 v69, vcc, 0, v67, vcc
	v_add_co_u32_e32 v70, vcc, s35, v66
	s_nop 1
	v_addc_co_u32_e32 v71, vcc, 0, v67, vcc
	flat_load_dwordx4 v[102:105], v[68:69] nt
	flat_load_dwordx4 v[98:101], v[70:71] nt
	v_add_co_u32_e32 v68, vcc, s36, v66
	s_nop 1
	v_addc_co_u32_e32 v69, vcc, 0, v67, vcc
	v_add_co_u32_e32 v70, vcc, s37, v66
	s_nop 1
	v_addc_co_u32_e32 v71, vcc, 0, v67, vcc
	flat_load_dwordx4 v[94:97], v[68:69] nt
	flat_load_dwordx4 v[90:93], v[70:71] nt
	v_add_co_u32_e32 v68, vcc, s38, v66
	s_nop 1
	v_addc_co_u32_e32 v69, vcc, 0, v67, vcc
	v_add_co_u32_e32 v70, vcc, s39, v66
	s_nop 1
	v_addc_co_u32_e32 v71, vcc, 0, v67, vcc
	flat_load_dwordx4 v[86:89], v[68:69] nt
	flat_load_dwordx4 v[82:85], v[70:71] nt
	v_add_co_u32_e32 v68, vcc, s40, v66
	s_nop 1
	v_addc_co_u32_e32 v69, vcc, 0, v67, vcc
	v_add_co_u32_e32 v70, vcc, 0x340000, v66
	s_nop 1
	v_addc_co_u32_e32 v71, vcc, 0, v67, vcc
	flat_load_dwordx4 v[78:81], v[68:69] nt
	flat_load_dwordx4 v[74:77], v[70:71] nt
	v_add_co_u32_e32 v68, vcc, 0x380000, v66
	s_nop 1
	v_addc_co_u32_e32 v69, vcc, 0, v67, vcc
	v_add_co_u32_e32 v66, vcc, 0x3c0000, v66
	s_nop 1
	v_addc_co_u32_e32 v67, vcc, 0, v67, vcc
	flat_load_dwordx4 v[70:73], v[68:69] nt
	s_nop 0
	flat_load_dwordx4 v[66:69], v[66:67] nt
	v_cmp_ne_u64_e32 vcc, 0, v[148:149]
	s_and_saveexec_b64 s[12:13], vcc
	s_xor_b64 s[12:13], exec, s[12:13]
	s_cbranch_execz .LBB0_150
	v_lshl_add_u64 v[156:157], v[148:149], 0, v[136:137]
	global_load_dword v248, v[156:157], off
	global_load_dword v249, v[156:157], off offset:16
	global_load_dword v250, v[156:157], off offset:32
	global_load_dword v251, v[156:157], off offset:48
	global_load_dword v252, v[156:157], off offset:64
	global_load_dword v253, v[156:157], off offset:80
	s_waitcnt vmcnt(0) lgkmcnt(0)
	v_pk_mul_f32 v[132:133], v[4:5], v[248:249] op_sel_hi:[1,0]
	v_pk_mul_f32 v[130:131], v[2:3], v[248:249] op_sel_hi:[1,0]
	ds_write_b128 v151, v[130:133]
	s_nop 1
	v_pk_mul_f32 v[132:133], v[8:9], v[248:249] op_sel:[0,1]
	v_pk_mul_f32 v[130:131], v[6:7], v[248:249] op_sel:[0,1]
	ds_write_b128 v151, v[130:133] offset:1088
	s_nop 1
	v_pk_mul_f32 v[132:133], v[12:13], v[250:251] op_sel_hi:[1,0]
	v_pk_mul_f32 v[130:131], v[10:11], v[250:251] op_sel_hi:[1,0]
	ds_write_b128 v151, v[130:133] offset:2176
	s_nop 1
	v_pk_mul_f32 v[132:133], v[16:17], v[250:251] op_sel:[0,1]
	v_pk_mul_f32 v[130:131], v[14:15], v[250:251] op_sel:[0,1]
	ds_write_b128 v151, v[130:133] offset:3264
	s_nop 1
	v_pk_mul_f32 v[132:133], v[20:21], v[252:253] op_sel_hi:[1,0]
	v_pk_mul_f32 v[130:131], v[18:19], v[252:253] op_sel_hi:[1,0]
	ds_write_b128 v151, v[130:133] offset:4352
	s_nop 1
	v_pk_mul_f32 v[132:133], v[24:25], v[252:253] op_sel:[0,1]
	v_pk_mul_f32 v[130:131], v[22:23], v[252:253] op_sel:[0,1]
	ds_write_b128 v151, v[130:133] offset:5440
	s_nop 1
	global_load_dword v248, v[156:157], off offset:96
	global_load_dword v249, v[156:157], off offset:112
	global_load_dword v250, v[156:157], off offset:128
	global_load_dword v251, v[156:157], off offset:144
	global_load_dword v252, v[156:157], off offset:160
	global_load_dword v253, v[156:157], off offset:176
	s_waitcnt vmcnt(0) lgkmcnt(0)
	v_pk_mul_f32 v[132:133], v[28:29], v[248:249] op_sel_hi:[1,0]
	v_pk_mul_f32 v[130:131], v[26:27], v[248:249] op_sel_hi:[1,0]
	ds_write_b128 v151, v[130:133] offset:6528
	s_nop 1
	v_pk_mul_f32 v[132:133], v[32:33], v[248:249] op_sel:[0,1]
	v_pk_mul_f32 v[130:131], v[30:31], v[248:249] op_sel:[0,1]
	ds_write_b128 v151, v[130:133] offset:7616
	s_nop 1
	v_pk_mul_f32 v[132:133], v[36:37], v[250:251] op_sel_hi:[1,0]
	v_pk_mul_f32 v[130:131], v[34:35], v[250:251] op_sel_hi:[1,0]
	ds_write_b128 v151, v[130:133] offset:8704
	s_nop 1
	v_pk_mul_f32 v[132:133], v[40:41], v[250:251] op_sel:[0,1]
	v_pk_mul_f32 v[130:131], v[38:39], v[250:251] op_sel:[0,1]
	ds_write_b128 v151, v[130:133] offset:9792
	s_nop 1
	v_pk_mul_f32 v[132:133], v[44:45], v[252:253] op_sel_hi:[1,0]
	v_pk_mul_f32 v[130:131], v[42:43], v[252:253] op_sel_hi:[1,0]
	ds_write_b128 v151, v[130:133] offset:10880
	s_nop 1
	v_pk_mul_f32 v[132:133], v[48:49], v[252:253] op_sel:[0,1]
	v_pk_mul_f32 v[130:131], v[46:47], v[252:253] op_sel:[0,1]
	ds_write_b128 v151, v[130:133] offset:11968
	s_nop 1
	global_load_dword v248, v[156:157], off offset:192
	global_load_dword v249, v[156:157], off offset:208
	global_load_dword v250, v[156:157], off offset:224
	global_load_dword v251, v[156:157], off offset:240
	s_waitcnt vmcnt(0) lgkmcnt(0)
	v_pk_mul_f32 v[132:133], v[52:53], v[248:249] op_sel_hi:[1,0]
	v_pk_mul_f32 v[130:131], v[50:51], v[248:249] op_sel_hi:[1,0]
	ds_write_b128 v151, v[130:133] offset:13056
	s_nop 1
	v_pk_mul_f32 v[132:133], v[56:57], v[248:249] op_sel:[0,1]
	v_pk_mul_f32 v[130:131], v[54:55], v[248:249] op_sel:[0,1]
	ds_write_b128 v151, v[130:133] offset:14144
	s_nop 1
	v_pk_mul_f32 v[132:133], v[60:61], v[250:251] op_sel_hi:[1,0]
	v_pk_mul_f32 v[130:131], v[58:59], v[250:251] op_sel_hi:[1,0]
	ds_write_b128 v151, v[130:133] offset:15232
	s_nop 1
	v_pk_mul_f32 v[132:133], v[64:65], v[250:251] op_sel:[0,1]
	v_pk_mul_f32 v[130:131], v[62:63], v[250:251] op_sel:[0,1]

; #define LAS __attribute__((address_space(3)))
; #define LDS_WAIT() asm volatile("s_waitcnt lgkmcnt(0)" ::: "memory")
; __device__ __forceinline__ void p0_finish(const P0Item& it, const f32x4 (&w)[16], LAS float* scr, int lane) {
;     const int c4 = (lane & 15) * 4, kr = lane >> 4;
;     if (it.gain) { const unsigned goff = (unsigned)(kr * 4);
; #pragma unroll
;         for (int i = 0; i < 16; ++i) { const float g = *(const float*)((const char*)(it.gain + 4 * i) + goff); *(LAS f32x4*)(scr + (kr + 4 * i) * 68 + c4) = w[i] * g; } }
;     else {
; #pragma unroll
;         for (int i = 0; i < 16; ++i) *(LAS f32x4*)(scr + (kr + 4 * i) * 68 + c4) = w[i]; }
;     LDS_WAIT(); asm volatile("" ::: "memory");
.LBB0_156:
	v_lshl_add_u64 v[156:157], s[8:9], 2, v[146:147]
	global_load_dword v248, v[156:157], off
	global_load_dword v249, v[156:157], off offset:16
	global_load_dword v250, v[156:157], off offset:32
	global_load_dword v251, v[156:157], off offset:48
	global_load_dword v252, v[156:157], off offset:64
	global_load_dword v253, v[156:157], off offset:80
	s_waitcnt vmcnt(0) lgkmcnt(0)
	v_pk_mul_f32 v[128:129], v[128:129], v[248:249] op_sel_hi:[1,0]
	v_pk_mul_f32 v[126:127], v[126:127], v[248:249] op_sel_hi:[1,0]
	ds_write_b128 v151, v[126:129]
	s_nop 1
	v_pk_mul_f32 v[124:125], v[124:125], v[248:249] op_sel:[0,1]
	v_pk_mul_f32 v[122:123], v[122:123], v[248:249] op_sel:[0,1]
	ds_write_b128 v151, v[122:125] offset:1088
	s_nop 1
	v_pk_mul_f32 v[120:121], v[120:121], v[250:251] op_sel_hi:[1,0]
	v_pk_mul_f32 v[118:119], v[118:119], v[250:251] op_sel_hi:[1,0]
	ds_write_b128 v151, v[118:121] offset:2176
	s_nop 1
	v_pk_mul_f32 v[116:117], v[116:117], v[250:251] op_sel:[0,1]
	v_pk_mul_f32 v[114:115], v[114:115], v[250:251] op_sel:[0,1]
	ds_write_b128 v151, v[114:117] offset:3264
	s_nop 1
	v_pk_mul_f32 v[112:113], v[112:113], v[252:253] op_sel_hi:[1,0]
	v_pk_mul_f32 v[110:111], v[110:111], v[252:253] op_sel_hi:[1,0]
	ds_write_b128 v151, v[110:113] offset:4352
	s_nop 1
	v_pk_mul_f32 v[108:109], v[108:109], v[252:253] op_sel:[0,1]
	v_pk_mul_f32 v[106:107], v[106:107], v[252:253] op_sel:[0,1]
	ds_write_b128 v151, v[106:109] offset:5440
	s_nop 1
	global_load_dword v248, v[156:157], off offset:96
	global_load_dword v249, v[156:157], off offset:112
	global_load_dword v250, v[156:157], off offset:128
	global_load_dword v251, v[156:157], off offset:144
	global_load_dword v252, v[156:157], off offset:160
	global_load_dword v253, v[156:157], off offset:176
	s_waitcnt vmcnt(0) lgkmcnt(0)
	v_pk_mul_f32 v[104:105], v[104:105], v[248:249] op_sel_hi:[1,0]
	v_pk_mul_f32 v[102:103], v[102:103], v[248:249] op_sel_hi:[1,0]
	ds_write_b128 v151, v[102:105] offset:6528
	s_nop 1
	v_pk_mul_f32 v[100:101], v[100:101], v[248:249] op_sel:[0,1]
	v_pk_mul_f32 v[98:99], v[98:99], v[248:249] op_sel:[0,1]
	ds_write_b128 v151, v[98:101] offset:7616
	s_nop 1
	v_pk_mul_f32 v[96:97], v[96:97], v[250:251] op_sel_hi:[1,0]
	v_pk_mul_f32 v[94:95], v[94:95], v[250:251] op_sel_hi:[1,0]
	ds_write_b128 v151, v[94:97] offset:8704
	s_nop 1
	v_pk_mul_f32 v[92:93], v[92:93], v[250:251] op_sel:[0,1]
	v_pk_mul_f32 v[90:91], v[90:91], v[250:251] op_sel:[0,1]
	ds_write_b128 v151, v[90:93] offset:9792
	s_nop 1
	v_pk_mul_f32 v[88:89], v[88:89], v[252:253] op_sel_hi:[1,0]
	v_pk_mul_f32 v[86:87], v[86:87], v[252:253] op_sel_hi:[1,0]
	ds_write_b128 v151, v[86:89] offset:10880
	s_nop 1
	v_pk_mul_f32 v[84:85], v[84:85], v[252:253] op_sel:[0,1]
	v_pk_mul_f32 v[82:83], v[82:83], v[252:253] op_sel:[0,1]
	ds_write_b128 v151, v[82:85] offset:11968
	s_nop 1
	global_load_dword v248, v[156:157], off offset:192
	global_load_dword v249, v[156:157], off offset:208
	global_load_dword v250, v[156:157], off offset:224
	global_load_dword v251, v[156:157], off offset:240
	s_waitcnt vmcnt(0) lgkmcnt(0)
	v_pk_mul_f32 v[80:81], v[80:81], v[248:249] op_sel_hi:[1,0]
	v_pk_mul_f32 v[78:79], v[78:79], v[248:249] op_sel_hi:[1,0]
	ds_write_b128 v151, v[78:81] offset:13056
	s_nop 1
	v_pk_mul_f32 v[76:77], v[76:77], v[248:249] op_sel:[0,1]
	v_pk_mul_f32 v[74:75], v[74:75], v[248:249] op_sel:[0,1]
	ds_write_b128 v151, v[74:77] offset:14144
	s_nop 1
	v_pk_mul_f32 v[72:73], v[72:73], v[250:251] op_sel_hi:[1,0]
	v_pk_mul_f32 v[70:71], v[70:71], v[250:251] op_sel_hi:[1,0]
	ds_write_b128 v151, v[70:73] offset:15232
	s_nop 1
	v_pk_mul_f32 v[68:69], v[68:69], v[250:251] op_sel:[0,1]
	v_pk_mul_f32 v[66:67], v[66:67], v[250:251] op_sel:[0,1]
	s_andn2_saveexec_b64 s[22:23], s[22:23]
	s_cbranch_execz .LBB0_147

; #define LAS __attribute__((address_space(3)))
; #define LDS_WAIT() asm volatile("s_waitcnt lgkmcnt(0)" ::: "memory")
; __device__ __forceinline__ void p0_load(const P0Item& it, f32x4 (&w)[16], int lane) {
;     const unsigned voff = (unsigned)(((lane >> 4) * it.ldw + (lane & 15) * 4) * 4);
; #pragma unroll
;     for (int i = 0; i < 16; ++i) w[i] = __builtin_nontemporal_load((const f32x4*)((const char*)(it.src + (size_t)(4 * i) * it.ldw) + voff));
; }
; __device__ __forceinline__ void p0_finish(const P0Item& it, const f32x4 (&w)[16], LAS float* scr, int lane) {
;     const int c4 = (lane & 15) * 4, kr = lane >> 4;
;     if (it.gain) { const unsigned goff = (unsigned)(kr * 4);
; #pragma unroll
;         for (int i = 0; i < 16; ++i) { const float g = *(const float*)((const char*)(it.gain + 4 * i) + goff); *(LAS f32x4*)(scr + (kr + 4 * i) * 68 + c4) = w[i] * g; } }
;     else {
; #pragma unroll
;         for (int i = 0; i < 16; ++i) *(LAS f32x4*)(scr + (kr + 4 * i) * 68 + c4) = w[i]; }
;     LDS_WAIT(); asm volatile("" ::: "memory");
.LBB0_260:
	s_add_i32 s10, s43, 0xfffff800
	s_ashr_i32 s11, s10, 31
	s_lshr_b32 s11, s11, 24
	s_add_i32 s11, s10, s11
	s_ashr_i32 s12, s11, 8
	s_and_b32 s11, s11, 0x3ffff00
	s_sub_i32 s11, s10, s11
	s_lshl_b32 s10, s12, 6
	s_lshl_b32 s12, s11, 6
	s_ashr_i32 s11, s10, 31
	s_lshl_b64 s[22:23], s[10:11], 16
	v_lshl_add_u64 v[66:67], v[138:139], 0, s[22:23]
	s_ashr_i32 s13, s12, 31
	v_lshl_add_u64 v[66:67], s[12:13], 2, v[66:67]
	v_lshl_add_u64 v[66:67], v[66:67], 0, v[140:141]
	v_add_co_u32_e32 v68, vcc, s28, v66
	s_nop 1
	v_addc_co_u32_e32 v69, vcc, 0, v67, vcc
	flat_load_dwordx4 v[126:129], v[66:67] nt
	flat_load_dwordx4 v[122:125], v[68:69] nt
	v_add_co_u32_e32 v68, vcc, s29, v66
	s_nop 1
	v_addc_co_u32_e32 v69, vcc, 0, v67, vcc
	v_add_co_u32_e32 v70, vcc, s30, v66
	s_nop 1
	v_addc_co_u32_e32 v71, vcc, 0, v67, vcc
	flat_load_dwordx4 v[118:121], v[68:69] nt
	flat_load_dwordx4 v[114:117], v[70:71] nt
	v_add_co_u32_e32 v68, vcc, s31, v66
	s_nop 1
	v_addc_co_u32_e32 v69, vcc, 0, v67, vcc
	v_add_co_u32_e32 v70, vcc, s34, v66
	s_nop 1
	v_addc_co_u32_e32 v71, vcc, 0, v67, vcc
	flat_load_dwordx4 v[110:113], v[68:69] nt
	flat_load_dwordx4 v[106:109], v[70:71] nt
	v_add_co_u32_e32 v68, vcc, s35, v66
	s_nop 1
	v_addc_co_u32_e32 v69, vcc, 0, v67, vcc
	v_add_co_u32_e32 v70, vcc, s36, v66
	s_nop 1
	v_addc_co_u32_e32 v71, vcc, 0, v67, vcc
	flat_load_dwordx4 v[102:105], v[68:69] nt
	flat_load_dwordx4 v[98:101], v[70:71] nt
	v_add_co_u32_e32 v68, vcc, s37, v66
	s_nop 1
	v_addc_co_u32_e32 v69, vcc, 0, v67, vcc
	v_add_co_u32_e32 v70, vcc, s38, v66
	s_nop 1
	v_addc_co_u32_e32 v71, vcc, 0, v67, vcc
	flat_load_dwordx4 v[94:97], v[68:69] nt
	flat_load_dwordx4 v[90:93], v[70:71] nt
	v_add_co_u32_e32 v68, vcc, s39, v66
	s_nop 1
	v_addc_co_u32_e32 v69, vcc, 0, v67, vcc
	v_add_co_u32_e32 v70, vcc, s40, v66
	s_nop 1
	v_addc_co_u32_e32 v71, vcc, 0, v67, vcc
	flat_load_dwordx4 v[86:89], v[68:69] nt
	flat_load_dwordx4 v[82:85], v[70:71] nt
	v_add_co_u32_e32 v68, vcc, s41, v66
	s_nop 1
	v_addc_co_u32_e32 v69, vcc, 0, v67, vcc
	v_add_co_u32_e32 v70, vcc, 0x340000, v66
	s_nop 1
	v_addc_co_u32_e32 v71, vcc, 0, v67, vcc
	flat_load_dwordx4 v[78:81], v[68:69] nt
	flat_load_dwordx4 v[74:77], v[70:71] nt
	v_add_co_u32_e32 v68, vcc, 0x380000, v66
	s_nop 1
	v_addc_co_u32_e32 v69, vcc, 0, v67, vcc
	v_add_co_u32_e32 v66, vcc, 0x3c0000, v66
	s_nop 1
	v_addc_co_u32_e32 v67, vcc, 0, v67, vcc
	flat_load_dwordx4 v[70:73], v[68:69] nt
	s_nop 0
	flat_load_dwordx4 v[66:69], v[66:67] nt
	v_cmp_ne_u64_e32 vcc, 0, v[148:149]
	s_and_saveexec_b64 s[22:23], vcc
	s_xor_b64 s[22:23], exec, s[22:23]
	s_cbranch_execz .LBB0_262
	v_lshl_add_u64 v[164:165], v[148:149], 0, v[136:137]
	global_load_dword v248, v[164:165], off
	global_load_dword v249, v[164:165], off offset:16
	global_load_dword v250, v[164:165], off offset:32
	global_load_dword v251, v[164:165], off offset:48
	global_load_dword v252, v[164:165], off offset:64
	global_load_dword v253, v[164:165], off offset:80
	s_waitcnt vmcnt(0) lgkmcnt(0)
	v_pk_mul_f32 v[132:133], v[4:5], v[248:249] op_sel_hi:[1,0]
	v_pk_mul_f32 v[130:131], v[2:3], v[248:249] op_sel_hi:[1,0]
	ds_write_b128 v151, v[130:133]
	s_nop 1
	v_pk_mul_f32 v[132:133], v[8:9], v[248:249] op_sel:[0,1]
	v_pk_mul_f32 v[130:131], v[6:7], v[248:249] op_sel:[0,1]
	ds_write_b128 v151, v[130:133] offset:1088
	s_nop 1
	v_pk_mul_f32 v[132:133], v[12:13], v[250:251] op_sel_hi:[1,0]
	v_pk_mul_f32 v[130:131], v[10:11], v[250:251] op_sel_hi:[1,0]
	ds_write_b128 v151, v[130:133] offset:2176
	s_nop 1
	v_pk_mul_f32 v[132:133], v[16:17], v[250:251] op_sel:[0,1]
	v_pk_mul_f32 v[130:131], v[14:15], v[250:251] op_sel:[0,1]
	ds_write_b128 v151, v[130:133] offset:3264
	s_nop 1
	v_pk_mul_f32 v[132:133], v[20:21], v[252:253] op_sel_hi:[1,0]
	v_pk_mul_f32 v[130:131], v[18:19], v[252:253] op_sel_hi:[1,0]
	ds_write_b128 v151, v[130:133] offset:4352
	s_nop 1
	v_pk_mul_f32 v[132:133], v[24:25], v[252:253] op_sel:[0,1]
	v_pk_mul_f32 v[130:131], v[22:23], v[252:253] op_sel:[0,1]
	ds_write_b128 v151, v[130:133] offset:5440
	s_nop 1
	global_load_dword v248, v[164:165], off offset:96
	global_load_dword v249, v[164:165], off offset:112
	global_load_dword v250, v[164:165], off offset:128
	global_load_dword v251, v[164:165], off offset:144
	global_load_dword v252, v[164:165], off offset:160
	global_load_dword v253, v[164:165], off offset:176
	s_waitcnt vmcnt(0) lgkmcnt(0)
	v_pk_mul_f32 v[132:133], v[28:29], v[248:249] op_sel_hi:[1,0]
	v_pk_mul_f32 v[130:131], v[26:27], v[248:249] op_sel_hi:[1,0]
	ds_write_b128 v151, v[130:133] offset:6528
	s_nop 1
	v_pk_mul_f32 v[132:133], v[32:33], v[248:249] op_sel:[0,1]
	v_pk_mul_f32 v[130:131], v[30:31], v[248:249] op_sel:[0,1]
	ds_write_b128 v151, v[130:133] offset:7616
	s_nop 1
	v_pk_mul_f32 v[132:133], v[36:37], v[250:251] op_sel_hi:[1,0]
	v_pk_mul_f32 v[130:131], v[34:35], v[250:251] op_sel_hi:[1,0]
	ds_write_b128 v151, v[130:133] offset:8704
	s_nop 1
	v_pk_mul_f32 v[132:133], v[40:41], v[250:251] op_sel:[0,1]
	v_pk_mul_f32 v[130:131], v[38:39], v[250:251] op_sel:[0,1]
	ds_write_b128 v151, v[130:133] offset:9792
	s_nop 1
	v_pk_mul_f32 v[132:133], v[44:45], v[252:253] op_sel_hi:[1,0]
	v_pk_mul_f32 v[130:131], v[42:43], v[252:253] op_sel_hi:[1,0]
	ds_write_b128 v151, v[130:133] offset:10880
	s_nop 1
	v_pk_mul_f32 v[132:133], v[48:49], v[252:253] op_sel:[0,1]
	v_pk_mul_f32 v[130:131], v[46:47], v[252:253] op_sel:[0,1]
	ds_write_b128 v151, v[130:133] offset:11968
	s_nop 1
	global_load_dword v248, v[164:165], off offset:192
	global_load_dword v249, v[164:165], off offset:208
	global_load_dword v250, v[164:165], off offset:224
	global_load_dword v251, v[164:165], off offset:240
	s_waitcnt vmcnt(0) lgkmcnt(0)
	v_pk_mul_f32 v[132:133], v[52:53], v[248:249] op_sel_hi:[1,0]
	v_pk_mul_f32 v[130:131], v[50:51], v[248:249] op_sel_hi:[1,0]
	ds_write_b128 v151, v[130:133] offset:13056
	s_nop 1
	v_pk_mul_f32 v[132:133], v[56:57], v[248:249] op_sel:[0,1]
	v_pk_mul_f32 v[130:131], v[54:55], v[248:249] op_sel:[0,1]
	ds_write_b128 v151, v[130:133] offset:14144
	s_nop 1
	v_pk_mul_f32 v[132:133], v[60:61], v[250:251] op_sel_hi:[1,0]
	v_pk_mul_f32 v[130:131], v[58:59], v[250:251] op_sel_hi:[1,0]
	ds_write_b128 v151, v[130:133] offset:15232
	s_nop 1
	v_pk_mul_f32 v[132:133], v[64:65], v[250:251] op_sel:[0,1]
	v_pk_mul_f32 v[130:131], v[62:63], v[250:251] op_sel:[0,1]

; #define LAS __attribute__((address_space(3)))
; #define LDS_WAIT() asm volatile("s_waitcnt lgkmcnt(0)" ::: "memory")
; __device__ __forceinline__ void p0_finish(const P0Item& it, const f32x4 (&w)[16], LAS float* scr, int lane) {
;     const int c4 = (lane & 15) * 4, kr = lane >> 4;
;     if (it.gain) { const unsigned goff = (unsigned)(kr * 4);
; #pragma unroll
;         for (int i = 0; i < 16; ++i) { const float g = *(const float*)((const char*)(it.gain + 4 * i) + goff); *(LAS f32x4*)(scr + (kr + 4 * i) * 68 + c4) = w[i] * g; } }
;     else {
; #pragma unroll
;         for (int i = 0; i < 16; ++i) *(LAS f32x4*)(scr + (kr + 4 * i) * 68 + c4) = w[i]; }
;     LDS_WAIT(); asm volatile("" ::: "memory");
.LBB0_268:
	v_lshl_add_u64 v[164:165], s[10:11], 2, v[146:147]
	global_load_dword v248, v[164:165], off
	global_load_dword v249, v[164:165], off offset:16
	global_load_dword v250, v[164:165], off offset:32
	global_load_dword v251, v[164:165], off offset:48
	global_load_dword v252, v[164:165], off offset:64
	global_load_dword v253, v[164:165], off offset:80
	s_waitcnt vmcnt(0) lgkmcnt(0)
	v_pk_mul_f32 v[128:129], v[128:129], v[248:249] op_sel_hi:[1,0]
	v_pk_mul_f32 v[126:127], v[126:127], v[248:249] op_sel_hi:[1,0]
	ds_write_b128 v151, v[126:129]
	s_nop 1
	v_pk_mul_f32 v[124:125], v[124:125], v[248:249] op_sel:[0,1]
	v_pk_mul_f32 v[122:123], v[122:123], v[248:249] op_sel:[0,1]
	ds_write_b128 v151, v[122:125] offset:1088
	s_nop 1
	v_pk_mul_f32 v[120:121], v[120:121], v[250:251] op_sel_hi:[1,0]
	v_pk_mul_f32 v[118:119], v[118:119], v[250:251] op_sel_hi:[1,0]
	ds_write_b128 v151, v[118:121] offset:2176
	s_nop 1
	v_pk_mul_f32 v[116:117], v[116:117], v[250:251] op_sel:[0,1]
	v_pk_mul_f32 v[114:115], v[114:115], v[250:251] op_sel:[0,1]
	ds_write_b128 v151, v[114:117] offset:3264
	s_nop 1
	v_pk_mul_f32 v[112:113], v[112:113], v[252:253] op_sel_hi:[1,0]
	v_pk_mul_f32 v[110:111], v[110:111], v[252:253] op_sel_hi:[1,0]
	ds_write_b128 v151, v[110:113] offset:4352
	s_nop 1
	v_pk_mul_f32 v[108:109], v[108:109], v[252:253] op_sel:[0,1]
	v_pk_mul_f32 v[106:107], v[106:107], v[252:253] op_sel:[0,1]
	ds_write_b128 v151, v[106:109] offset:5440
	s_nop 1
	global_load_dword v248, v[164:165], off offset:96
	global_load_dword v249, v[164:165], off offset:112
	global_load_dword v250, v[164:165], off offset:128
	global_load_dword v251, v[164:165], off offset:144
	global_load_dword v252, v[164:165], off offset:160
	global_load_dword v253, v[164:165], off offset:176
	s_waitcnt vmcnt(0) lgkmcnt(0)
	v_pk_mul_f32 v[104:105], v[104:105], v[248:249] op_sel_hi:[1,0]
	v_pk_mul_f32 v[102:103], v[102:103], v[248:249] op_sel_hi:[1,0]
	ds_write_b128 v151, v[102:105] offset:6528
	s_nop 1
	v_pk_mul_f32 v[100:101], v[100:101], v[248:249] op_sel:[0,1]
	v_pk_mul_f32 v[98:99], v[98:99], v[248:249] op_sel:[0,1]
	ds_write_b128 v151, v[98:101] offset:7616
	s_nop 1
	v_pk_mul_f32 v[96:97], v[96:97], v[250:251] op_sel_hi:[1,0]
	v_pk_mul_f32 v[94:95], v[94:95], v[250:251] op_sel_hi:[1,0]
	ds_write_b128 v151, v[94:97] offset:8704
	s_nop 1
	v_pk_mul_f32 v[92:93], v[92:93], v[250:251] op_sel:[0,1]
	v_pk_mul_f32 v[90:91], v[90:91], v[250:251] op_sel:[0,1]
	ds_write_b128 v151, v[90:93] offset:9792
	s_nop 1
	v_pk_mul_f32 v[88:89], v[88:89], v[252:253] op_sel_hi:[1,0]
	v_pk_mul_f32 v[86:87], v[86:87], v[252:253] op_sel_hi:[1,0]
	ds_write_b128 v151, v[86:89] offset:10880
	s_nop 1
	v_pk_mul_f32 v[84:85], v[84:85], v[252:253] op_sel:[0,1]
	v_pk_mul_f32 v[82:83], v[82:83], v[252:253] op_sel:[0,1]
	ds_write_b128 v151, v[82:85] offset:11968
	s_nop 1
	global_load_dword v248, v[164:165], off offset:192
	global_load_dword v249, v[164:165], off offset:208
	global_load_dword v250, v[164:165], off offset:224
	global_load_dword v251, v[164:165], off offset:240
	s_waitcnt vmcnt(0) lgkmcnt(0)
	v_pk_mul_f32 v[80:81], v[80:81], v[248:249] op_sel_hi:[1,0]
	v_pk_mul_f32 v[78:79], v[78:79], v[248:249] op_sel_hi:[1,0]
	ds_write_b128 v151, v[78:81] offset:13056
	s_nop 1
	v_pk_mul_f32 v[76:77], v[76:77], v[248:249] op_sel:[0,1]
	v_pk_mul_f32 v[74:75], v[74:75], v[248:249] op_sel:[0,1]
	ds_write_b128 v151, v[74:77] offset:14144
	s_nop 1
	v_pk_mul_f32 v[72:73], v[72:73], v[250:251] op_sel_hi:[1,0]
	v_pk_mul_f32 v[70:71], v[70:71], v[250:251] op_sel_hi:[1,0]
	ds_write_b128 v151, v[70:73] offset:15232
	s_nop 1
	v_pk_mul_f32 v[68:69], v[68:69], v[250:251] op_sel:[0,1]
	v_pk_mul_f32 v[66:67], v[66:67], v[250:251] op_sel:[0,1]
	s_andn2_saveexec_b64 s[24:25], s[24:25]
	s_cbranch_execz .LBB0_259

; #define LAS __attribute__((address_space(3)))
; #define LDS_WAIT() asm volatile("s_waitcnt lgkmcnt(0)" ::: "memory")
; __device__ __forceinline__ void p0_load(const P0Item& it, f32x4 (&w)[16], int lane) {
;     const unsigned voff = (unsigned)(((lane >> 4) * it.ldw + (lane & 15) * 4) * 4);
; #pragma unroll
;     for (int i = 0; i < 16; ++i) w[i] = __builtin_nontemporal_load((const f32x4*)((const char*)(it.src + (size_t)(4 * i) * it.ldw) + voff));
; }
; __device__ __forceinline__ void p0_finish(const P0Item& it, const f32x4 (&w)[16], LAS float* scr, int lane) {
;     const int c4 = (lane & 15) * 4, kr = lane >> 4;
;     if (it.gain) { const unsigned goff = (unsigned)(kr * 4);
; #pragma unroll
;         for (int i = 0; i < 16; ++i) { const float g = *(const float*)((const char*)(it.gain + 4 * i) + goff); *(LAS f32x4*)(scr + (kr + 4 * i) * 68 + c4) = w[i] * g; } }
;     else {
; #pragma unroll
;         for (int i = 0; i < 16; ++i) *(LAS f32x4*)(scr + (kr + 4 * i) * 68 + c4) = w[i]; }
;     LDS_WAIT(); asm volatile("" ::: "memory");
.LBB0_458:
	s_add_i32 s8, s41, 0xfffff800
	s_ashr_i32 s9, s8, 31
	s_lshr_b32 s9, s9, 24
	s_add_i32 s9, s8, s9
	s_ashr_i32 s10, s9, 8
	s_and_b32 s9, s9, 0x3ffff00
	s_sub_i32 s9, s8, s9
	s_lshl_b32 s8, s10, 6
	s_lshl_b32 s10, s9, 6
	s_ashr_i32 s9, s8, 31
	s_lshl_b64 s[12:13], s[8:9], 16
	v_lshl_add_u64 v[66:67], v[138:139], 0, s[12:13]
	s_ashr_i32 s11, s10, 31
	v_lshl_add_u64 v[66:67], s[10:11], 2, v[66:67]
	v_lshl_add_u64 v[66:67], v[66:67], 0, v[140:141]
	v_add_co_u32_e32 v68, vcc, s26, v66
	s_nop 1
	v_addc_co_u32_e32 v69, vcc, 0, v67, vcc
	flat_load_dwordx4 v[126:129], v[66:67] nt
	flat_load_dwordx4 v[122:125], v[68:69] nt
	v_add_co_u32_e32 v68, vcc, s27, v66
	s_nop 1
	v_addc_co_u32_e32 v69, vcc, 0, v67, vcc
	v_add_co_u32_e32 v70, vcc, s28, v66
	s_nop 1
	v_addc_co_u32_e32 v71, vcc, 0, v67, vcc
	flat_load_dwordx4 v[118:121], v[68:69] nt
	flat_load_dwordx4 v[114:117], v[70:71] nt
	v_add_co_u32_e32 v68, vcc, s29, v66
	s_nop 1
	v_addc_co_u32_e32 v69, vcc, 0, v67, vcc
	v_add_co_u32_e32 v70, vcc, s30, v66
	s_nop 1
	v_addc_co_u32_e32 v71, vcc, 0, v67, vcc
	flat_load_dwordx4 v[110:113], v[68:69] nt
	flat_load_dwordx4 v[106:109], v[70:71] nt
	v_add_co_u32_e32 v68, vcc, s31, v66
	s_nop 1
	v_addc_co_u32_e32 v69, vcc, 0, v67, vcc
	v_add_co_u32_e32 v70, vcc, s34, v66
	s_nop 1
	v_addc_co_u32_e32 v71, vcc, 0, v67, vcc
	flat_load_dwordx4 v[102:105], v[68:69] nt
	flat_load_dwordx4 v[98:101], v[70:71] nt
	v_add_co_u32_e32 v68, vcc, s35, v66
	s_nop 1
	v_addc_co_u32_e32 v69, vcc, 0, v67, vcc
	v_add_co_u32_e32 v70, vcc, s36, v66
	s_nop 1
	v_addc_co_u32_e32 v71, vcc, 0, v67, vcc
	flat_load_dwordx4 v[94:97], v[68:69] nt
	flat_load_dwordx4 v[90:93], v[70:71] nt
	v_add_co_u32_e32 v68, vcc, s37, v66
	s_nop 1
	v_addc_co_u32_e32 v69, vcc, 0, v67, vcc
	v_add_co_u32_e32 v70, vcc, s38, v66
	s_nop 1
	v_addc_co_u32_e32 v71, vcc, 0, v67, vcc
	flat_load_dwordx4 v[86:89], v[68:69] nt
	flat_load_dwordx4 v[82:85], v[70:71] nt
	v_add_co_u32_e32 v68, vcc, s39, v66
	s_nop 1
	v_addc_co_u32_e32 v69, vcc, 0, v67, vcc
	v_add_co_u32_e32 v70, vcc, 0x340000, v66
	s_nop 1
	v_addc_co_u32_e32 v71, vcc, 0, v67, vcc
	flat_load_dwordx4 v[78:81], v[68:69] nt
	flat_load_dwordx4 v[74:77], v[70:71] nt
	v_add_co_u32_e32 v68, vcc, 0x380000, v66
	s_nop 1
	v_addc_co_u32_e32 v69, vcc, 0, v67, vcc
	v_add_co_u32_e32 v66, vcc, 0x3c0000, v66
	s_nop 1
	v_addc_co_u32_e32 v67, vcc, 0, v67, vcc
	flat_load_dwordx4 v[70:73], v[68:69] nt
	s_nop 0
	flat_load_dwordx4 v[66:69], v[66:67] nt
	v_cmp_ne_u64_e32 vcc, 0, v[148:149]
	s_and_saveexec_b64 s[12:13], vcc
	s_xor_b64 s[12:13], exec, s[12:13]
	s_cbranch_execz .LBB0_460
	v_lshl_add_u64 v[156:157], v[148:149], 0, v[136:137]
	global_load_dword v248, v[156:157], off
	global_load_dword v249, v[156:157], off offset:16
	global_load_dword v250, v[156:157], off offset:32
	global_load_dword v251, v[156:157], off offset:48
	global_load_dword v252, v[156:157], off offset:64
	global_load_dword v253, v[156:157], off offset:80
	s_waitcnt vmcnt(0) lgkmcnt(0)
	v_pk_mul_f32 v[132:133], v[4:5], v[248:249] op_sel_hi:[1,0]
	v_pk_mul_f32 v[130:131], v[2:3], v[248:249] op_sel_hi:[1,0]
	ds_write_b128 v151, v[130:133]
	s_nop 1
	v_pk_mul_f32 v[132:133], v[8:9], v[248:249] op_sel:[0,1]
	v_pk_mul_f32 v[130:131], v[6:7], v[248:249] op_sel:[0,1]
	ds_write_b128 v151, v[130:133] offset:1088
	s_nop 1
	v_pk_mul_f32 v[132:133], v[12:13], v[250:251] op_sel_hi:[1,0]
	v_pk_mul_f32 v[130:131], v[10:11], v[250:251] op_sel_hi:[1,0]
	ds_write_b128 v151, v[130:133] offset:2176
	s_nop 1
	v_pk_mul_f32 v[132:133], v[16:17], v[250:251] op_sel:[0,1]
	v_pk_mul_f32 v[130:131], v[14:15], v[250:251] op_sel:[0,1]
	ds_write_b128 v151, v[130:133] offset:3264
	s_nop 1
	v_pk_mul_f32 v[132:133], v[20:21], v[252:253] op_sel_hi:[1,0]
	v_pk_mul_f32 v[130:131], v[18:19], v[252:253] op_sel_hi:[1,0]
	ds_write_b128 v151, v[130:133] offset:4352
	s_nop 1
	v_pk_mul_f32 v[132:133], v[24:25], v[252:253] op_sel:[0,1]
	v_pk_mul_f32 v[130:131], v[22:23], v[252:253] op_sel:[0,1]
	ds_write_b128 v151, v[130:133] offset:5440
	s_nop 1
	global_load_dword v248, v[156:157], off offset:96
	global_load_dword v249, v[156:157], off offset:112
	global_load_dword v250, v[156:157], off offset:128
	global_load_dword v251, v[156:157], off offset:144
	global_load_dword v252, v[156:157], off offset:160
	global_load_dword v253, v[156:157], off offset:176
	s_waitcnt vmcnt(0) lgkmcnt(0)
	v_pk_mul_f32 v[132:133], v[28:29], v[248:249] op_sel_hi:[1,0]
	v_pk_mul_f32 v[130:131], v[26:27], v[248:249] op_sel_hi:[1,0]
	ds_write_b128 v151, v[130:133] offset:6528
	s_nop 1
	v_pk_mul_f32 v[132:133], v[32:33], v[248:249] op_sel:[0,1]
	v_pk_mul_f32 v[130:131], v[30:31], v[248:249] op_sel:[0,1]
	ds_write_b128 v151, v[130:133] offset:7616
	s_nop 1
	v_pk_mul_f32 v[132:133], v[36:37], v[250:251] op_sel_hi:[1,0]
	v_pk_mul_f32 v[130:131], v[34:35], v[250:251] op_sel_hi:[1,0]
	ds_write_b128 v151, v[130:133] offset:8704
	s_nop 1
	v_pk_mul_f32 v[132:133], v[40:41], v[250:251] op_sel:[0,1]
	v_pk_mul_f32 v[130:131], v[38:39], v[250:251] op_sel:[0,1]
	ds_write_b128 v151, v[130:133] offset:9792
	s_nop 1
	v_pk_mul_f32 v[132:133], v[44:45], v[252:253] op_sel_hi:[1,0]
	v_pk_mul_f32 v[130:131], v[42:43], v[252:253] op_sel_hi:[1,0]
	ds_write_b128 v151, v[130:133] offset:10880
	s_nop 1
	v_pk_mul_f32 v[132:133], v[48:49], v[252:253] op_sel:[0,1]
	v_pk_mul_f32 v[130:131], v[46:47], v[252:253] op_sel:[0,1]
	ds_write_b128 v151, v[130:133] offset:11968
	s_nop 1
	global_load_dword v248, v[156:157], off offset:192
	global_load_dword v249, v[156:157], off offset:208
	global_load_dword v250, v[156:157], off offset:224
	global_load_dword v251, v[156:157], off offset:240
	s_waitcnt vmcnt(0) lgkmcnt(0)
	v_pk_mul_f32 v[132:133], v[52:53], v[248:249] op_sel_hi:[1,0]
	v_pk_mul_f32 v[130:131], v[50:51], v[248:249] op_sel_hi:[1,0]
	ds_write_b128 v151, v[130:133] offset:13056
	s_nop 1
	v_pk_mul_f32 v[132:133], v[56:57], v[248:249] op_sel:[0,1]
	v_pk_mul_f32 v[130:131], v[54:55], v[248:249] op_sel:[0,1]
	ds_write_b128 v151, v[130:133] offset:14144
	s_nop 1
	v_pk_mul_f32 v[132:133], v[60:61], v[250:251] op_sel_hi:[1,0]
	v_pk_mul_f32 v[130:131], v[58:59], v[250:251] op_sel_hi:[1,0]
	ds_write_b128 v151, v[130:133] offset:15232
	s_nop 1
	v_pk_mul_f32 v[132:133], v[64:65], v[250:251] op_sel:[0,1]
	v_pk_mul_f32 v[130:131], v[62:63], v[250:251] op_sel:[0,1]

; #define LAS __attribute__((address_space(3)))
; __device__ __forceinline__ int crow(int r, int hi) { return (r & 3) + 8 * (r >> 2) + 4 * hi; }
; __device__ __forceinline__ int crow(int r, int hi) { return (r & 3) + 8 * (r >> 2) + 4 * hi; }
; __device__ __forceinline__ void gc_unit(LAS unsigned char* lds, int unit, const bf16_t* proj, const bf16_t* dSt, const float* gnorm, bf16_t* omix, int tid, int wave, int lane) {
;     ...
;       for (int ss = 0; ss < 4; ++ss) { const bf16x8 a0 = *(const LAS bf16x8*)(lds + L_AT + r * 144 + ss * 32 + hh * 16), a1 = *(const LAS bf16x8*)(lds + L_AT + (32 + r) * 144 + ss * 32 + hh * 16);
;           o0 = __builtin_amdgcn_mfma_f32_32x32x16_bf16(a0, vf[ss], o0, 0, 0, 0); o1 = __builtin_amdgcn_mfma_f32_32x32x16_bf16(a1, vf[ss], o1, 0, 0, 0); } }
;     {
; #pragma unroll
;       for (int ks = 0; ks < 8; ++ks) { const bf16x8 bb = sfr[ks];
;           const bf16x8 a0 = *(const LAS bf16x8*)(lds + L_QD + r * 272 + ks * 32 + hh * 16), a1 = *(const LAS bf16x8*)(lds + L_QD + (32 + r) * 272 + ks * 32 + hh * 16);
;           o0 = __builtin_amdgcn_mfma_f32_32x32x16_bf16(a0, bb, o0, 0, 0, 0); o1 = __builtin_amdgcn_mfma_f32_32x32x16_bf16(a1, bb, o1, 0, 0, 0); } }
;     __syncthreads();
; #pragma unroll
;     for (int i = 0; i < 16; ++i) { const int c = crow(i, hh); *(LAS float*)(lds + L_OT + c * 1040 + (32 * wave + r) * 4) = o0[i]; *(LAS float*)(lds + L_OT + (32 + c) * 1040 + (32 * wave + r) * 4) = o1[i]; }
;     __syncthreads();
;     const f32x4 g = *((const f32x4*)gnorm + lane);
; #pragma unroll
;     for (int rr = 0; rr < 8; ++rr) { const int c = 8 * wave + rr; const f32x4 v = *(const LAS f32x4*)(lds + L_OT + c * 1040 + lane * 16);
;         float ss = (v[0] * v[0] + v[1] * v[1]) + (v[2] * v[2] + v[3] * v[3]);
; #pragma unroll
;         for (int o = 1; o < 64; o <<= 1) ss += __shfl_xor(ss, o);
;         const float rs = 1.0f / sqrtf(ss * (1.0f / 256.0f) + EPS);
;         const u32x2 gw2 = *((const u32x2*)(proj + (row0 + c) * PROJ_LD + C_GOUT + h * 256) + lane);
.LBB0_1008:
	ds_read_b128 v[2:5], v105
	ds_read_b128 v[114:117], v105 offset:32
	ds_read_b128 v[22:25], v106
	ds_read_b128 v[118:121], v106 offset:32
	s_lshl_b32 s38, s38, 1
	s_add_u32 s50, s48, s33
	s_waitcnt lgkmcnt(3)
	v_mfma_f32_32x32x16_bf16 v[2:17], v[2:5], v[18:21], 0
	s_addc_u32 s51, s49, 0
	s_mul_i32 s40, s51, 0x3000
	s_mul_hi_u32 s41, s50, 0x3000
	s_add_i32 s41, s41, s40
	s_mul_i32 s40, s50, 0x3000
	s_add_u32 s40, s90, s40
	s_addc_u32 s41, s91, s41
	s_waitcnt lgkmcnt(1)
	v_mfma_f32_32x32x16_bf16 v[18:33], v[22:25], v[18:21], 0
	v_lshlrev_b32_e32 v78, 4, v182
	s_add_u32 s40, s40, s38
	s_addc_u32 s41, s41, 0
	v_lshlrev_b32_e32 v122, 3, v182
	v_add_u32_e32 v122, 0x2000, v122
	v_mov_b32_e32 v123, 0
	v_mov_b32_e32 v124, 0x3000
	v_mov_b32_e32 v125, 0
	v_lshl_add_u64 v[122:123], s[40:41], 0, v[122:123]
	global_load_dwordx2 v[126:127], v[122:123], off
	v_lshl_add_u64 v[122:123], v[122:123], 0, v[124:125]
	global_load_dwordx2 v[128:129], v[122:123], off
	v_lshl_add_u64 v[122:123], v[122:123], 0, v[124:125]
	global_load_dwordx2 v[130:131], v[122:123], off
	v_lshl_add_u64 v[122:123], v[122:123], 0, v[124:125]
	global_load_dwordx2 v[132:133], v[122:123], off
	v_lshl_add_u64 v[122:123], v[122:123], 0, v[124:125]
	global_load_dwordx2 v[134:135], v[122:123], off
	v_lshl_add_u64 v[122:123], v[122:123], 0, v[124:125]
	global_load_dwordx2 v[136:137], v[122:123], off
	v_lshl_add_u64 v[122:123], v[122:123], 0, v[124:125]
	global_load_dwordx2 v[138:139], v[122:123], off
	v_lshl_add_u64 v[122:123], v[122:123], 0, v[124:125]
	global_load_dwordx2 v[140:141], v[122:123], off
	v_lshl_add_u64 v[84:85], v[84:85], 0, s[44:45]
	v_mfma_f32_32x32x16_bf16 v[2:17], v[114:117], v[74:77], v[2:17]
	s_waitcnt lgkmcnt(0)
	v_mfma_f32_32x32x16_bf16 v[18:33], v[118:121], v[74:77], v[18:33]
	ds_read_b128 v[74:77], v105 offset:64
	ds_read_b128 v[114:117], v105 offset:96
	s_waitcnt lgkmcnt(1)
	v_mfma_f32_32x32x16_bf16 v[2:17], v[74:77], v[70:73], v[2:17]
	ds_read_b128 v[74:77], v106 offset:64
	ds_read_b128 v[118:121], v106 offset:96
	s_waitcnt lgkmcnt(1)
	v_mfma_f32_32x32x16_bf16 v[18:33], v[74:77], v[70:73], v[18:33]
	v_mfma_f32_32x32x16_bf16 v[2:17], v[114:117], v[66:69], v[2:17]
	s_waitcnt lgkmcnt(0)
	v_mfma_f32_32x32x16_bf16 v[18:33], v[118:121], v[66:69], v[18:33]
	ds_read_b128 v[66:69], v107 offset:4096
	ds_read_b128 v[70:73], v107 offset:4128
	s_waitcnt lgkmcnt(1)
	v_mfma_f32_32x32x16_bf16 v[2:17], v[66:69], v[38:41], v[2:17]
	ds_read_b128 v[66:69], v108 offset:4096
	ds_read_b128 v[74:77], v108 offset:4128
	s_waitcnt lgkmcnt(1)
	v_mfma_f32_32x32x16_bf16 v[18:33], v[66:69], v[38:41], v[18:33]
	v_mfma_f32_32x32x16_bf16 v[2:17], v[70:73], v[34:37], v[2:17]
	s_waitcnt lgkmcnt(0)
	v_mfma_f32_32x32x16_bf16 v[18:33], v[74:77], v[34:37], v[18:33]
	ds_read_b128 v[34:37], v107 offset:4160
	ds_read_b128 v[38:41], v107 offset:4192
	s_waitcnt lgkmcnt(1)
	v_mfma_f32_32x32x16_bf16 v[2:17], v[34:37], v[62:65], v[2:17]
	ds_read_b128 v[34:37], v108 offset:4160
	ds_read_b128 v[66:69], v108 offset:4192
	s_waitcnt lgkmcnt(1)
	v_mfma_f32_32x32x16_bf16 v[18:33], v[34:37], v[62:65], v[18:33]
	v_mfma_f32_32x32x16_bf16 v[2:17], v[38:41], v[58:61], v[2:17]
	ds_read_b128 v[34:37], v107 offset:4224
	ds_read_b128 v[38:41], v107 offset:4256
	s_waitcnt lgkmcnt(2)
	v_mfma_f32_32x32x16_bf16 v[18:33], v[66:69], v[58:61], v[18:33]
	s_waitcnt lgkmcnt(1)
	v_mfma_f32_32x32x16_bf16 v[2:17], v[34:37], v[54:57], v[2:17]
	ds_read_b128 v[34:37], v108 offset:4224
	ds_read_b128 v[58:61], v108 offset:4256
	s_waitcnt lgkmcnt(1)
	v_mfma_f32_32x32x16_bf16 v[18:33], v[34:37], v[54:57], v[18:33]
	v_mfma_f32_32x32x16_bf16 v[2:17], v[38:41], v[50:53], v[2:17]
	ds_read_b128 v[34:37], v107 offset:4288
	ds_read_b128 v[38:41], v107 offset:4320
	s_waitcnt lgkmcnt(2)
	v_mfma_f32_32x32x16_bf16 v[18:33], v[58:61], v[50:53], v[18:33]
	s_waitcnt lgkmcnt(1)
	v_mfma_f32_32x32x16_bf16 v[2:17], v[34:37], v[46:49], v[2:17]
	ds_read_b128 v[34:37], v108 offset:4288
	ds_read_b128 v[50:53], v108 offset:4320
	s_waitcnt lgkmcnt(0)
	s_barrier
	v_mfma_f32_32x32x16_bf16 v[18:33], v[34:37], v[46:49], v[18:33]
	v_mfma_f32_32x32x16_bf16 v[2:17], v[38:41], v[42:45], v[2:17]
	v_mfma_f32_32x32x16_bf16 v[18:33], v[50:53], v[42:45], v[18:33]
	s_nop 10
	ds_write_b32 v109, v2 offset:4096
	v_add_u32_e32 v2, s52, v98
	ds_write_b32 v109, v18 offset:37376
	ds_write_b32 v109, v3 offset:5136
	ds_write_b32 v109, v19 offset:38416
	ds_write_b32 v109, v4 offset:6176
	ds_write_b32 v109, v20 offset:39456
	ds_write_b32 v109, v5 offset:7216
	ds_write_b32 v109, v21 offset:40496
	ds_write_b32 v109, v6 offset:12416
	ds_write_b32 v109, v22 offset:45696
	ds_write_b32 v109, v7 offset:13456
	ds_write_b32 v109, v23 offset:46736
	ds_write_b32 v109, v8 offset:14496
	ds_write_b32 v109, v24 offset:47776
	ds_write_b32 v109, v9 offset:15536
	ds_write_b32 v109, v25 offset:48816
	ds_write_b32 v109, v10 offset:20736
	ds_write_b32 v109, v26 offset:54016
	ds_write_b32 v109, v11 offset:21776
	ds_write_b32 v109, v27 offset:55056
	ds_write_b32 v109, v12 offset:22816
	ds_write_b32 v109, v28 offset:56096
	ds_write_b32 v109, v13 offset:23856
	ds_write_b32 v109, v29 offset:57136
	ds_write_b32 v109, v14 offset:29056
	ds_write_b32 v109, v30 offset:62336
	ds_write_b32 v109, v15 offset:30096
	ds_write_b32 v109, v31 offset:63376
	ds_write_b32 v109, v16 offset:31136
	ds_write_b32 v109, v32 offset:64416
	ds_write_b32 v109, v17 offset:32176
	ds_write_b32 v109, v33 offset:65456
	s_waitcnt lgkmcnt(0)
	s_barrier
; #define LAS __attribute__((address_space(3)))
; __device__ __forceinline__ unsigned cvt_pk_bf16(float lo, float hi) { unsigned r; asm volatile("v_cvt_pk_bf16_f32 %0, %1, %2" : "=v"(r) : "v"(lo), "v"(hi)); return r; }
; __device__ __forceinline__ float bflo(unsigned w) { return __uint_as_float(w << 16); }
; __device__ __forceinline__ float bfhi(unsigned w) { return __uint_as_float(w & 0xffff0000u); }
; __device__ __forceinline__ void gc_unit(LAS unsigned char* lds, int unit, const bf16_t* proj, const bf16_t* dSt, const float* gnorm, bf16_t* omix, int tid, int wave, int lane) {
;     ...
;     const f32x4 g = *((const f32x4*)gnorm + lane);
; #pragma unroll
;     for (int rr = 0; rr < 8; ++rr) { const int c = 8 * wave + rr; const f32x4 v = *(const LAS f32x4*)(lds + L_OT + c * 1040 + lane * 16);
;         float ss = (v[0] * v[0] + v[1] * v[1]) + (v[2] * v[2] + v[3] * v[3]);
; #pragma unroll
;         for (int o = 1; o < 64; o <<= 1) ss += __shfl_xor(ss, o);
;         const float rs = 1.0f / sqrtf(ss * (1.0f / 256.0f) + EPS);
;         const u32x2 gw2 = *((const u32x2*)(proj + (row0 + c) * PROJ_LD + C_GOUT + h * 256) + lane);
;         const float z0 = bflo(gw2.x), z1 = bfhi(gw2.x), z2 = bflo(gw2.y), z3 = bfhi(gw2.y);
;         const float p0 = v[0] * rs * g[0] * (z0 / (1.0f + __expf(-z0))), p1 = v[1] * rs * g[1] * (z1 / (1.0f + __expf(-z1)));
;         const float p2 = v[2] * rs * g[2] * (z2 / (1.0f + __expf(-z2))), p3 = v[3] * rs * g[3] * (z3 / (1.0f + __expf(-z3)));
;         u32x2 w; w.x = cvt_pk_bf16(p0, p1); w.y = cvt_pk_bf16(p2, p3); *((u32x2*)(omix + (row0 + c) * DM + h * 256) + lane) = w; }
	ds_read_b128 v[14:17], v2 offset:4096
	v_and_b32_e32 v2, 64, v112
	v_add_u32_e32 v6, 64, v2
	s_waitcnt lgkmcnt(0)
	v_mul_f32_e32 v2, v15, v15
	v_mul_f32_e32 v3, v17, v17
	v_fmac_f32_e32 v2, v14, v14
	v_fmac_f32_e32 v3, v16, v16
	v_add_f32_e32 v4, v2, v3
	v_xor_b32_e32 v2, 1, v112
	v_cmp_lt_i32_e32 vcc, v2, v6
	s_nop 1
	v_cndmask_b32_e32 v2, v112, v2, vcc
	v_lshlrev_b32_e32 v8, 2, v2
	ds_bpermute_b32 v5, v8, v4
	v_lshl_add_u64 v[2:3], v[96:97], 0, v[78:79]
	v_lshlrev_b32_e32 v78, 3, v182
	s_waitcnt lgkmcnt(0)
	v_add_f32_e32 v7, v4, v5
	v_xor_b32_e32 v4, 2, v112
	v_cmp_lt_i32_e32 vcc, v4, v6
	s_nop 1
	v_cndmask_b32_e32 v4, v112, v4, vcc
	v_lshlrev_b32_e32 v9, 2, v4
	v_lshl_add_u64 v[4:5], s[40:41], 0, v[78:79]
	v_add_co_u32_e32 v4, vcc, s66, v4
	ds_bpermute_b32 v10, v9, v7
	s_nop 0
	v_addc_co_u32_e32 v5, vcc, 0, v5, vcc
	v_xor_b32_e32 v4, 4, v112
	v_cmp_lt_i32_e32 vcc, v4, v6
	s_waitcnt lgkmcnt(0)
	v_add_f32_e32 v7, v7, v10
	v_cndmask_b32_e32 v4, v112, v4, vcc
	v_lshlrev_b32_e32 v10, 2, v4
	ds_bpermute_b32 v11, v10, v7
	flat_load_dwordx4 v[2:5], v[2:3]
	s_waitcnt lgkmcnt(0)
	v_add_f32_e32 v7, v7, v11
	v_xor_b32_e32 v11, 8, v112
	v_cmp_lt_i32_e32 vcc, v11, v6
	s_nop 1
	v_cndmask_b32_e32 v11, v112, v11, vcc
	v_lshlrev_b32_e32 v11, 2, v11
	ds_bpermute_b32 v12, v11, v7
	s_waitcnt lgkmcnt(0)
	v_add_f32_e32 v7, v7, v12
	v_xor_b32_e32 v12, 16, v112
	v_cmp_lt_i32_e32 vcc, v12, v6
	s_nop 1
	v_cndmask_b32_e32 v12, v112, v12, vcc
	v_lshlrev_b32_e32 v12, 2, v12
	ds_bpermute_b32 v13, v12, v7
	s_waitcnt lgkmcnt(0)
	v_add_f32_e32 v7, v7, v13
	v_xor_b32_e32 v13, 32, v112
	v_cmp_lt_i32_e32 vcc, v13, v6
	s_nop 1
	v_cndmask_b32_e32 v6, v112, v13, vcc
	v_lshlrev_b32_e32 v13, 2, v6
	ds_bpermute_b32 v6, v13, v7
	s_waitcnt lgkmcnt(0)
	v_add_f32_e32 v6, v7, v6
	v_fmamk_f32 v6, v6, 0x3b800000, v110
	v_mul_f32_e32 v7, 0x4f800000, v6
	v_cmp_gt_f32_e32 vcc, s65, v6
	s_nop 1
	v_cndmask_b32_e32 v6, v6, v7, vcc
	v_sqrt_f32_e32 v7, v6
	s_nop 0
	v_add_u32_e32 v20, -1, v7
	v_fma_f32 v21, -v20, v7, v6
	v_cmp_ge_f32_e64 s[40:41], 0, v21
	v_add_u32_e32 v21, 1, v7
	s_nop 0
	v_cndmask_b32_e64 v20, v7, v20, s[40:41]
	v_fma_f32 v7, -v21, v7, v6
	v_cmp_lt_f32_e64 s[40:41], 0, v7
	s_nop 1
	v_cndmask_b32_e64 v7, v20, v21, s[40:41]
	v_mul_f32_e32 v20, 0x37800000, v7
	v_cndmask_b32_e32 v7, v7, v20, vcc
	v_cmp_class_f32_e32 vcc, v6, v111
	s_nop 1
	v_cndmask_b32_e32 v20, v7, v6, vcc
	v_div_scale_f32 v21, s[40:41], v20, v20, 1.0
	v_rcp_f32_e32 v22, v21
	v_lshl_add_u64 v[6:7], v[82:83], 0, s[38:39]
	v_fma_f32 v23, -v21, v22, 1.0
	v_fmac_f32_e32 v22, v23, v22
	v_div_scale_f32 v23, vcc, 1.0, v20, 1.0
	v_mul_f32_e32 v24, v23, v22
	v_fma_f32 v25, -v21, v24, v23
	v_fmac_f32_e32 v24, v25, v22
	v_fma_f32 v21, -v21, v24, v23
	v_div_fmas_f32 v21, v21, v22, v24
	s_waitcnt vmcnt(0)
	v_mov_b32_e32 v18, v126
	v_mov_b32_e32 v19, v127
	v_lshlrev_b32_e32 v22, 16, v18
	v_mul_f32_e32 v23, 0xbfb8aa3b, v22
	v_exp_f32_e32 v23, v23
	v_div_fixup_f32 v20, v21, v20, 1.0
	v_and_b32_e32 v18, 0xffff0000, v18
	v_mul_f32_e32 v14, v14, v20
	v_add_f32_e32 v21, 1.0, v23
	v_div_scale_f32 v23, s[40:41], v21, v21, v22
	v_rcp_f32_e32 v24, v23
	v_mul_f32_e32 v14, v2, v14
	v_lshlrev_b32_e32 v25, 16, v19
	v_mul_f32_e32 v15, v15, v20
	v_fma_f32 v26, -v23, v24, 1.0
	v_fmac_f32_e32 v24, v26, v24
	v_div_scale_f32 v26, vcc, v22, v21, v22
	v_mul_f32_e32 v27, v26, v24
	v_fma_f32 v28, -v23, v27, v26
	v_fmac_f32_e32 v27, v28, v24
	v_fma_f32 v23, -v23, v27, v26
	v_mul_f32_e32 v26, 0xbfb8aa3b, v18
	v_exp_f32_e32 v26, v26
	v_div_fmas_f32 v23, v23, v24, v27
	v_div_fixup_f32 v21, v23, v21, v22
	v_mul_f32_e32 v14, v21, v14
	v_add_f32_e32 v22, 1.0, v26
	v_div_scale_f32 v23, s[40:41], v22, v22, v18
	v_rcp_f32_e32 v24, v23
	v_mul_f32_e32 v15, v3, v15
	v_and_b32_e32 v19, 0xffff0000, v19
	v_mul_f32_e32 v16, v16, v20
	v_fma_f32 v21, -v23, v24, 1.0
	v_fmac_f32_e32 v24, v21, v24
	v_div_scale_f32 v21, vcc, v18, v22, v18
	v_mul_f32_e32 v26, v21, v24
	v_fma_f32 v27, -v23, v26, v21
	v_fmac_f32_e32 v26, v27, v24
	v_fma_f32 v21, -v23, v26, v21
	v_mul_f32_e32 v23, 0xbfb8aa3b, v25
	v_exp_f32_e32 v23, v23
	v_div_fmas_f32 v21, v21, v24, v26
	v_div_fixup_f32 v18, v21, v22, v18
	v_mul_f32_e32 v15, v18, v15
	v_add_f32_e32 v21, 1.0, v23
	v_div_scale_f32 v22, s[40:41], v21, v21, v25
	v_rcp_f32_e32 v23, v22
	v_mul_f32_e32 v16, v4, v16
	v_mul_f32_e32 v17, v17, v20
	v_mul_f32_e32 v17, v5, v17
	v_fma_f32 v18, -v22, v23, 1.0
	v_fmac_f32_e32 v23, v18, v23
	v_div_scale_f32 v18, vcc, v25, v21, v25
	v_mul_f32_e32 v24, v18, v23
	v_fma_f32 v26, -v22, v24, v18
	v_fmac_f32_e32 v24, v26, v23
	v_fma_f32 v18, -v22, v24, v18
	v_mul_f32_e32 v22, 0xbfb8aa3b, v19
	v_exp_f32_e32 v22, v22
	v_div_fmas_f32 v18, v18, v23, v24
	v_div_fixup_f32 v18, v18, v21, v25
	v_mul_f32_e32 v16, v18, v16
	v_add_f32_e32 v21, 1.0, v22
	v_div_scale_f32 v22, s[40:41], v21, v21, v19
	v_rcp_f32_e32 v23, v22
	s_lshl_b64 s[40:41], s[50:51], 13
	s_add_u32 s50, s48, s53
	s_addc_u32 s51, s49, 0
	v_fma_f32 v18, -v22, v23, 1.0
	v_fmac_f32_e32 v23, v18, v23
	v_div_scale_f32 v18, vcc, v19, v21, v19
	v_mul_f32_e32 v20, v18, v23
	v_fma_f32 v24, -v22, v20, v18
	v_fmac_f32_e32 v20, v24, v23
	v_fma_f32 v18, -v22, v20, v18
	v_div_fmas_f32 v18, v18, v23, v20
	v_div_fixup_f32 v18, v18, v21, v19
	v_mul_f32_e32 v17, v18, v17
	v_cvt_pk_bf16_f32 v14, v14, v15
	v_cvt_pk_bf16_f32 v15, v16, v17
	v_lshl_add_u64 v[16:17], v[6:7], 0, s[40:41]
	s_mul_i32 s40, s51, 0x3000
	s_mul_hi_u32 s41, s50, 0x3000
	s_add_i32 s41, s41, s40
	s_mul_i32 s40, s50, 0x3000
	s_add_u32 s40, s90, s40
	s_addc_u32 s41, s91, s41
	s_add_u32 s40, s40, s38
	s_addc_u32 s41, s41, 0
	v_lshl_add_u64 v[20:21], s[40:41], 0, v[78:79]
	v_add_co_u32_e32 v20, vcc, s66, v20
	global_store_dwordx2 v[16:17], v[14:15], off
	s_nop 0
	v_addc_co_u32_e32 v21, vcc, 0, v21, vcc
	v_add_u32_e32 v14, s54, v98
	ds_read_b128 v[16:19], v14 offset:4096
	s_waitcnt lgkmcnt(0)
; #define LAS __attribute__((address_space(3)))
; __device__ __forceinline__ unsigned cvt_pk_bf16(float lo, float hi) { unsigned r; asm volatile("v_cvt_pk_bf16_f32 %0, %1, %2" : "=v"(r) : "v"(lo), "v"(hi)); return r; }
; __device__ __forceinline__ float bflo(unsigned w) { return __uint_as_float(w << 16); }
; __device__ __forceinline__ float bfhi(unsigned w) { return __uint_as_float(w & 0xffff0000u); }
; __device__ __forceinline__ void gc_unit(LAS unsigned char* lds, int unit, const bf16_t* proj, const bf16_t* dSt, const float* gnorm, bf16_t* omix, int tid, int wave, int lane) {
;     ...
;     for (int rr = 0; rr < 8; ++rr) { const int c = 8 * wave + rr; const f32x4 v = *(const LAS f32x4*)(lds + L_OT + c * 1040 + lane * 16);
;         float ss = (v[0] * v[0] + v[1] * v[1]) + (v[2] * v[2] + v[3] * v[3]);
; #pragma unroll
;         for (int o = 1; o < 64; o <<= 1) ss += __shfl_xor(ss, o);
;         const float rs = 1.0f / sqrtf(ss * (1.0f / 256.0f) + EPS);
;         const u32x2 gw2 = *((const u32x2*)(proj + (row0 + c) * PROJ_LD + C_GOUT + h * 256) + lane);
;         const float z0 = bflo(gw2.x), z1 = bfhi(gw2.x), z2 = bflo(gw2.y), z3 = bfhi(gw2.y);
;         const float p0 = v[0] * rs * g[0] * (z0 / (1.0f + __expf(-z0))), p1 = v[1] * rs * g[1] * (z1 / (1.0f + __expf(-z1)));
;         const float p2 = v[2] * rs * g[2] * (z2 / (1.0f + __expf(-z2))), p3 = v[3] * rs * g[3] * (z3 / (1.0f + __expf(-z3)));
;         u32x2 w; w.x = cvt_pk_bf16(p0, p1); w.y = cvt_pk_bf16(p2, p3); *((u32x2*)(omix + (row0 + c) * DM + h * 256) + lane) = w; }
	v_mul_f32_e32 v15, v17, v17
	v_mul_f32_e32 v22, v19, v19
	v_fmac_f32_e32 v15, v16, v16
	v_fmac_f32_e32 v22, v18, v18
	v_add_f32_e32 v15, v15, v22
	ds_bpermute_b32 v22, v8, v15
	s_waitcnt lgkmcnt(0)
	v_add_f32_e32 v15, v15, v22
	ds_bpermute_b32 v22, v9, v15
	s_waitcnt lgkmcnt(0)
	v_add_f32_e32 v15, v15, v22
	ds_bpermute_b32 v22, v10, v15
	s_waitcnt lgkmcnt(0)
	v_add_f32_e32 v15, v15, v22
	ds_bpermute_b32 v22, v11, v15
	s_waitcnt lgkmcnt(0)
	v_add_f32_e32 v15, v15, v22
	ds_bpermute_b32 v22, v12, v15
	s_waitcnt lgkmcnt(0)
	v_add_f32_e32 v15, v15, v22
	ds_bpermute_b32 v22, v13, v15
	s_waitcnt lgkmcnt(0)
	v_add_f32_e32 v15, v15, v22
	v_fmamk_f32 v15, v15, 0x3b800000, v110
	v_mul_f32_e32 v22, 0x4f800000, v15
	v_cmp_gt_f32_e32 vcc, s65, v15
	s_nop 1
	v_cndmask_b32_e32 v15, v15, v22, vcc
	v_sqrt_f32_e32 v22, v15
	s_nop 0
	v_add_u32_e32 v23, -1, v22
	v_fma_f32 v24, -v23, v22, v15
	v_cmp_ge_f32_e64 s[40:41], 0, v24
	v_add_u32_e32 v24, 1, v22
	s_nop 0
	v_cndmask_b32_e64 v23, v22, v23, s[40:41]
	v_fma_f32 v22, -v24, v22, v15
	v_cmp_lt_f32_e64 s[40:41], 0, v22
	s_nop 1
	v_cndmask_b32_e64 v22, v23, v24, s[40:41]
	v_mul_f32_e32 v23, 0x37800000, v22
	v_cndmask_b32_e32 v22, v22, v23, vcc
	v_cmp_class_f32_e32 vcc, v15, v111
	s_nop 1
	v_cndmask_b32_e32 v15, v22, v15, vcc
	v_div_scale_f32 v22, s[40:41], v15, v15, 1.0
	v_rcp_f32_e32 v23, v22
	s_nop 0
	v_fma_f32 v24, -v22, v23, 1.0
	v_fmac_f32_e32 v23, v24, v23
	v_div_scale_f32 v24, vcc, 1.0, v15, 1.0
	v_mul_f32_e32 v25, v24, v23
	v_fma_f32 v26, -v22, v25, v24
	v_fmac_f32_e32 v25, v26, v23
	v_fma_f32 v22, -v22, v25, v24
	v_div_fmas_f32 v22, v22, v23, v25
	v_mov_b32_e32 v20, v128
	v_mov_b32_e32 v21, v129
	v_lshlrev_b32_e32 v23, 16, v20
	v_mul_f32_e32 v24, 0xbfb8aa3b, v23
	v_exp_f32_e32 v24, v24
	v_and_b32_e32 v20, 0xffff0000, v20
	v_div_fixup_f32 v15, v22, v15, 1.0
	v_mul_f32_e32 v16, v16, v15
	v_add_f32_e32 v24, 1.0, v24
	v_div_scale_f32 v25, s[40:41], v24, v24, v23
	v_rcp_f32_e32 v26, v25
	v_mul_f32_e32 v16, v2, v16
	v_lshlrev_b32_e32 v22, 16, v21
	v_mul_f32_e32 v17, v17, v15
	v_fma_f32 v27, -v25, v26, 1.0
	v_fmac_f32_e32 v26, v27, v26
	v_div_scale_f32 v27, vcc, v23, v24, v23
	v_mul_f32_e32 v28, v27, v26
	v_fma_f32 v29, -v25, v28, v27
	v_fmac_f32_e32 v28, v29, v26
	v_fma_f32 v25, -v25, v28, v27
	v_mul_f32_e32 v27, 0xbfb8aa3b, v20
	v_exp_f32_e32 v27, v27
	v_div_fmas_f32 v25, v25, v26, v28
	v_div_fixup_f32 v23, v25, v24, v23
	v_mul_f32_e32 v16, v23, v16
	v_add_f32_e32 v24, 1.0, v27
	v_div_scale_f32 v25, s[40:41], v24, v24, v20
	v_rcp_f32_e32 v26, v25
	v_mul_f32_e32 v17, v3, v17
	v_and_b32_e32 v21, 0xffff0000, v21
	v_mul_f32_e32 v18, v18, v15
	v_fma_f32 v23, -v25, v26, 1.0
	v_fmac_f32_e32 v26, v23, v26
	v_div_scale_f32 v23, vcc, v20, v24, v20
	v_mul_f32_e32 v27, v23, v26
	v_fma_f32 v28, -v25, v27, v23
	v_fmac_f32_e32 v27, v28, v26
	v_fma_f32 v23, -v25, v27, v23
	v_mul_f32_e32 v25, 0xbfb8aa3b, v22
	v_exp_f32_e32 v25, v25
	v_div_fmas_f32 v23, v23, v26, v27
	v_div_fixup_f32 v20, v23, v24, v20
	v_mul_f32_e32 v17, v20, v17
	v_add_f32_e32 v23, 1.0, v25
	v_div_scale_f32 v24, s[40:41], v23, v23, v22
	v_rcp_f32_e32 v25, v24
	v_mul_f32_e32 v15, v19, v15
	v_mul_f32_e32 v18, v4, v18
	v_mul_f32_e32 v15, v5, v15
	v_fma_f32 v20, -v24, v25, 1.0
	v_fmac_f32_e32 v25, v20, v25
	v_div_scale_f32 v20, vcc, v22, v23, v22
	v_mul_f32_e32 v26, v20, v25
	v_fma_f32 v27, -v24, v26, v20
	v_fmac_f32_e32 v26, v27, v25
	v_fma_f32 v20, -v24, v26, v20
	v_mul_f32_e32 v24, 0xbfb8aa3b, v21
	v_exp_f32_e32 v24, v24
	v_div_fmas_f32 v20, v20, v25, v26
	v_div_fixup_f32 v20, v20, v23, v22
	v_mul_f32_e32 v18, v20, v18
	v_add_f32_e32 v22, 1.0, v24
	v_div_scale_f32 v23, s[40:41], v22, v22, v21
	v_rcp_f32_e32 v24, v23
	s_lshl_b64 s[40:41], s[50:51], 13
	s_add_u32 s50, s48, s55
	s_addc_u32 s51, s49, 0
	v_fma_f32 v19, -v23, v24, 1.0
	v_fmac_f32_e32 v24, v19, v24
	v_div_scale_f32 v19, vcc, v21, v22, v21
	v_mul_f32_e32 v20, v19, v24
	v_fma_f32 v25, -v23, v20, v19
	v_fmac_f32_e32 v20, v25, v24
	v_fma_f32 v19, -v23, v20, v19
	v_div_fmas_f32 v19, v19, v24, v20
	v_div_fixup_f32 v19, v19, v22, v21
	v_mul_f32_e32 v15, v19, v15
	v_cvt_pk_bf16_f32 v16, v16, v17
	v_cvt_pk_bf16_f32 v17, v18, v15
	v_lshl_add_u64 v[18:19], v[6:7], 0, s[40:41]
	s_mul_i32 s40, s51, 0x3000
	s_mul_hi_u32 s41, s50, 0x3000
	s_add_i32 s41, s41, s40
	s_mul_i32 s40, s50, 0x3000
	s_add_u32 s40, s90, s40
	s_addc_u32 s41, s91, s41
	s_add_u32 s40, s40, s38
	s_addc_u32 s41, s41, 0
	v_lshl_add_u64 v[20:21], s[40:41], 0, v[78:79]
	v_add_co_u32_e32 v20, vcc, s66, v20
	global_store_dwordx2 v[18:19], v[16:17], off
	s_nop 0
	v_addc_co_u32_e32 v21, vcc, 0, v21, vcc
	ds_read_b128 v[16:19], v14 offset:5136
	s_waitcnt lgkmcnt(0)
	v_mul_f32_e32 v15, v17, v17
	v_mul_f32_e32 v22, v19, v19
	v_fmac_f32_e32 v15, v16, v16
	v_fmac_f32_e32 v22, v18, v18
	v_add_f32_e32 v15, v15, v22
	ds_bpermute_b32 v22, v8, v15
	s_waitcnt lgkmcnt(0)
	v_add_f32_e32 v15, v15, v22
	ds_bpermute_b32 v22, v9, v15
	s_waitcnt lgkmcnt(0)
	v_add_f32_e32 v15, v15, v22
	ds_bpermute_b32 v22, v10, v15
	s_waitcnt lgkmcnt(0)
	v_add_f32_e32 v15, v15, v22
	ds_bpermute_b32 v22, v11, v15
	s_waitcnt lgkmcnt(0)
	v_add_f32_e32 v15, v15, v22
	ds_bpermute_b32 v22, v12, v15
	s_waitcnt lgkmcnt(0)
	v_add_f32_e32 v15, v15, v22
	ds_bpermute_b32 v22, v13, v15
	s_waitcnt lgkmcnt(0)
; #define LAS __attribute__((address_space(3)))
; __device__ __forceinline__ unsigned cvt_pk_bf16(float lo, float hi) { unsigned r; asm volatile("v_cvt_pk_bf16_f32 %0, %1, %2" : "=v"(r) : "v"(lo), "v"(hi)); return r; }
; __device__ __forceinline__ float bflo(unsigned w) { return __uint_as_float(w << 16); }
; __device__ __forceinline__ float bfhi(unsigned w) { return __uint_as_float(w & 0xffff0000u); }
; __device__ __forceinline__ void gc_unit(LAS unsigned char* lds, int unit, const bf16_t* proj, const bf16_t* dSt, const float* gnorm, bf16_t* omix, int tid, int wave, int lane) {
;     ...
;     for (int rr = 0; rr < 8; ++rr) { const int c = 8 * wave + rr; const f32x4 v = *(const LAS f32x4*)(lds + L_OT + c * 1040 + lane * 16);
;         float ss = (v[0] * v[0] + v[1] * v[1]) + (v[2] * v[2] + v[3] * v[3]);
; #pragma unroll
;         for (int o = 1; o < 64; o <<= 1) ss += __shfl_xor(ss, o);
;         const float rs = 1.0f / sqrtf(ss * (1.0f / 256.0f) + EPS);
;         const u32x2 gw2 = *((const u32x2*)(proj + (row0 + c) * PROJ_LD + C_GOUT + h * 256) + lane);
;         const float z0 = bflo(gw2.x), z1 = bfhi(gw2.x), z2 = bflo(gw2.y), z3 = bfhi(gw2.y);
;         const float p0 = v[0] * rs * g[0] * (z0 / (1.0f + __expf(-z0))), p1 = v[1] * rs * g[1] * (z1 / (1.0f + __expf(-z1)));
;         const float p2 = v[2] * rs * g[2] * (z2 / (1.0f + __expf(-z2))), p3 = v[3] * rs * g[3] * (z3 / (1.0f + __expf(-z3)));
;         u32x2 w; w.x = cvt_pk_bf16(p0, p1); w.y = cvt_pk_bf16(p2, p3); *((u32x2*)(omix + (row0 + c) * DM + h * 256) + lane) = w; }
	v_add_f32_e32 v15, v15, v22
	v_fmamk_f32 v15, v15, 0x3b800000, v110
	v_mul_f32_e32 v22, 0x4f800000, v15
	v_cmp_gt_f32_e32 vcc, s65, v15
	s_nop 1
	v_cndmask_b32_e32 v15, v15, v22, vcc
	v_sqrt_f32_e32 v22, v15
	s_nop 0
	v_add_u32_e32 v23, -1, v22
	v_fma_f32 v24, -v23, v22, v15
	v_cmp_ge_f32_e64 s[40:41], 0, v24
	v_add_u32_e32 v24, 1, v22
	s_nop 0
	v_cndmask_b32_e64 v23, v22, v23, s[40:41]
	v_fma_f32 v22, -v24, v22, v15
	v_cmp_lt_f32_e64 s[40:41], 0, v22
	s_nop 1
	v_cndmask_b32_e64 v22, v23, v24, s[40:41]
	v_mul_f32_e32 v23, 0x37800000, v22
	v_cndmask_b32_e32 v22, v22, v23, vcc
	v_cmp_class_f32_e32 vcc, v15, v111
	s_nop 1
	v_cndmask_b32_e32 v15, v22, v15, vcc
	v_div_scale_f32 v22, s[40:41], v15, v15, 1.0
	v_rcp_f32_e32 v23, v22
	s_nop 0
	v_fma_f32 v24, -v22, v23, 1.0
	v_fmac_f32_e32 v23, v24, v23
	v_div_scale_f32 v24, vcc, 1.0, v15, 1.0
	v_mul_f32_e32 v25, v24, v23
	v_fma_f32 v26, -v22, v25, v24
	v_fmac_f32_e32 v25, v26, v23
	v_fma_f32 v22, -v22, v25, v24
	v_div_fmas_f32 v22, v22, v23, v25
	v_mov_b32_e32 v20, v130
	v_mov_b32_e32 v21, v131
	v_lshlrev_b32_e32 v23, 16, v20
	v_mul_f32_e32 v24, 0xbfb8aa3b, v23
	v_exp_f32_e32 v24, v24
	v_and_b32_e32 v20, 0xffff0000, v20
	v_div_fixup_f32 v15, v22, v15, 1.0
	v_mul_f32_e32 v16, v16, v15
	v_add_f32_e32 v24, 1.0, v24
	v_div_scale_f32 v25, s[40:41], v24, v24, v23
	v_rcp_f32_e32 v26, v25
	v_mul_f32_e32 v16, v2, v16
	v_lshlrev_b32_e32 v22, 16, v21
	v_mul_f32_e32 v17, v17, v15
	v_fma_f32 v27, -v25, v26, 1.0
	v_fmac_f32_e32 v26, v27, v26
	v_div_scale_f32 v27, vcc, v23, v24, v23
	v_mul_f32_e32 v28, v27, v26
	v_fma_f32 v29, -v25, v28, v27
	v_fmac_f32_e32 v28, v29, v26
	v_fma_f32 v25, -v25, v28, v27
	v_mul_f32_e32 v27, 0xbfb8aa3b, v20
	v_exp_f32_e32 v27, v27
	v_div_fmas_f32 v25, v25, v26, v28
	v_div_fixup_f32 v23, v25, v24, v23
	v_mul_f32_e32 v16, v23, v16
	v_add_f32_e32 v24, 1.0, v27
	v_div_scale_f32 v25, s[40:41], v24, v24, v20
	v_rcp_f32_e32 v26, v25
	v_mul_f32_e32 v17, v3, v17
	v_and_b32_e32 v21, 0xffff0000, v21
	v_mul_f32_e32 v18, v18, v15
	v_fma_f32 v23, -v25, v26, 1.0
	v_fmac_f32_e32 v26, v23, v26
	v_div_scale_f32 v23, vcc, v20, v24, v20
	v_mul_f32_e32 v27, v23, v26
	v_fma_f32 v28, -v25, v27, v23
	v_fmac_f32_e32 v27, v28, v26
	v_fma_f32 v23, -v25, v27, v23
	v_mul_f32_e32 v25, 0xbfb8aa3b, v22
	v_exp_f32_e32 v25, v25
	v_div_fmas_f32 v23, v23, v26, v27
	v_div_fixup_f32 v20, v23, v24, v20
	v_mul_f32_e32 v17, v20, v17
	v_add_f32_e32 v23, 1.0, v25
	v_div_scale_f32 v24, s[40:41], v23, v23, v22
	v_rcp_f32_e32 v25, v24
	v_mul_f32_e32 v15, v19, v15
	v_mul_f32_e32 v18, v4, v18
	v_mul_f32_e32 v15, v5, v15
	v_fma_f32 v20, -v24, v25, 1.0
	v_fmac_f32_e32 v25, v20, v25
	v_div_scale_f32 v20, vcc, v22, v23, v22
	v_mul_f32_e32 v26, v20, v25
	v_fma_f32 v27, -v24, v26, v20
	v_fmac_f32_e32 v26, v27, v25
	v_fma_f32 v20, -v24, v26, v20
	v_mul_f32_e32 v24, 0xbfb8aa3b, v21
	v_exp_f32_e32 v24, v24
	v_div_fmas_f32 v20, v20, v25, v26
	v_div_fixup_f32 v20, v20, v23, v22
	v_mul_f32_e32 v18, v20, v18
	v_add_f32_e32 v22, 1.0, v24
	v_div_scale_f32 v23, s[40:41], v22, v22, v21
	v_rcp_f32_e32 v24, v23
	s_lshl_b64 s[40:41], s[50:51], 13
	s_add_u32 s50, s48, s56
	s_addc_u32 s51, s49, 0
	v_fma_f32 v19, -v23, v24, 1.0
	v_fmac_f32_e32 v24, v19, v24
	v_div_scale_f32 v19, vcc, v21, v22, v21
	v_mul_f32_e32 v20, v19, v24
	v_fma_f32 v25, -v23, v20, v19
	v_fmac_f32_e32 v20, v25, v24
	v_fma_f32 v19, -v23, v20, v19
	v_div_fmas_f32 v19, v19, v24, v20
	v_div_fixup_f32 v19, v19, v22, v21
	v_mul_f32_e32 v15, v19, v15
	v_cvt_pk_bf16_f32 v16, v16, v17
	v_cvt_pk_bf16_f32 v17, v18, v15
	v_lshl_add_u64 v[18:19], v[6:7], 0, s[40:41]
	s_mul_i32 s40, s51, 0x3000
	s_mul_hi_u32 s41, s50, 0x3000
	s_add_i32 s41, s41, s40
	s_mul_i32 s40, s50, 0x3000
	s_add_u32 s40, s90, s40
	s_addc_u32 s41, s91, s41
	s_add_u32 s40, s40, s38
	s_addc_u32 s41, s41, 0
	v_lshl_add_u64 v[20:21], s[40:41], 0, v[78:79]
	v_add_co_u32_e32 v20, vcc, s66, v20
	global_store_dwordx2 v[18:19], v[16:17], off
	s_nop 0
	v_addc_co_u32_e32 v21, vcc, 0, v21, vcc
	ds_read_b128 v[16:19], v14 offset:6176
	s_waitcnt lgkmcnt(0)
	v_mul_f32_e32 v15, v17, v17
	v_mul_f32_e32 v22, v19, v19
	v_fmac_f32_e32 v15, v16, v16
	v_fmac_f32_e32 v22, v18, v18
	v_add_f32_e32 v15, v15, v22
	ds_bpermute_b32 v22, v8, v15
	s_waitcnt lgkmcnt(0)
	v_add_f32_e32 v15, v15, v22
	ds_bpermute_b32 v22, v9, v15
	s_waitcnt lgkmcnt(0)
	v_add_f32_e32 v15, v15, v22
	ds_bpermute_b32 v22, v10, v15
	s_waitcnt lgkmcnt(0)
	v_add_f32_e32 v15, v15, v22
	ds_bpermute_b32 v22, v11, v15
	s_waitcnt lgkmcnt(0)
	v_add_f32_e32 v15, v15, v22
	ds_bpermute_b32 v22, v12, v15
	s_waitcnt lgkmcnt(0)
	v_add_f32_e32 v15, v15, v22
	ds_bpermute_b32 v22, v13, v15
	s_waitcnt lgkmcnt(0)
; #define LAS __attribute__((address_space(3)))
; __device__ __forceinline__ unsigned cvt_pk_bf16(float lo, float hi) { unsigned r; asm volatile("v_cvt_pk_bf16_f32 %0, %1, %2" : "=v"(r) : "v"(lo), "v"(hi)); return r; }
; __device__ __forceinline__ float bflo(unsigned w) { return __uint_as_float(w << 16); }
; __device__ __forceinline__ float bfhi(unsigned w) { return __uint_as_float(w & 0xffff0000u); }
; __device__ __forceinline__ void gc_unit(LAS unsigned char* lds, int unit, const bf16_t* proj, const bf16_t* dSt, const float* gnorm, bf16_t* omix, int tid, int wave, int lane) {
;     ...
;     for (int rr = 0; rr < 8; ++rr) { const int c = 8 * wave + rr; const f32x4 v = *(const LAS f32x4*)(lds + L_OT + c * 1040 + lane * 16);
;         float ss = (v[0] * v[0] + v[1] * v[1]) + (v[2] * v[2] + v[3] * v[3]);
; #pragma unroll
;         for (int o = 1; o < 64; o <<= 1) ss += __shfl_xor(ss, o);
;         const float rs = 1.0f / sqrtf(ss * (1.0f / 256.0f) + EPS);
;         const u32x2 gw2 = *((const u32x2*)(proj + (row0 + c) * PROJ_LD + C_GOUT + h * 256) + lane);
;         const float z0 = bflo(gw2.x), z1 = bfhi(gw2.x), z2 = bflo(gw2.y), z3 = bfhi(gw2.y);
;         const float p0 = v[0] * rs * g[0] * (z0 / (1.0f + __expf(-z0))), p1 = v[1] * rs * g[1] * (z1 / (1.0f + __expf(-z1)));
;         const float p2 = v[2] * rs * g[2] * (z2 / (1.0f + __expf(-z2))), p3 = v[3] * rs * g[3] * (z3 / (1.0f + __expf(-z3)));
;         u32x2 w; w.x = cvt_pk_bf16(p0, p1); w.y = cvt_pk_bf16(p2, p3); *((u32x2*)(omix + (row0 + c) * DM + h * 256) + lane) = w; }
	v_add_f32_e32 v15, v15, v22
	v_fmamk_f32 v15, v15, 0x3b800000, v110
	v_mul_f32_e32 v22, 0x4f800000, v15
	v_cmp_gt_f32_e32 vcc, s65, v15
	s_nop 1
	v_cndmask_b32_e32 v15, v15, v22, vcc
	v_sqrt_f32_e32 v22, v15
	s_nop 0
	v_add_u32_e32 v23, -1, v22
	v_fma_f32 v24, -v23, v22, v15
	v_cmp_ge_f32_e64 s[40:41], 0, v24
	v_add_u32_e32 v24, 1, v22
	s_nop 0
	v_cndmask_b32_e64 v23, v22, v23, s[40:41]
	v_fma_f32 v22, -v24, v22, v15
	v_cmp_lt_f32_e64 s[40:41], 0, v22
	s_nop 1
	v_cndmask_b32_e64 v22, v23, v24, s[40:41]
	v_mul_f32_e32 v23, 0x37800000, v22
	v_cndmask_b32_e32 v22, v22, v23, vcc
	v_cmp_class_f32_e32 vcc, v15, v111
	s_nop 1
	v_cndmask_b32_e32 v15, v22, v15, vcc
	v_div_scale_f32 v22, s[40:41], v15, v15, 1.0
	v_rcp_f32_e32 v23, v22
	s_nop 0
	v_fma_f32 v24, -v22, v23, 1.0
	v_fmac_f32_e32 v23, v24, v23
	v_div_scale_f32 v24, vcc, 1.0, v15, 1.0
	v_mul_f32_e32 v25, v24, v23
	v_fma_f32 v26, -v22, v25, v24
	v_fmac_f32_e32 v25, v26, v23
	v_fma_f32 v22, -v22, v25, v24
	v_div_fmas_f32 v22, v22, v23, v25
	v_mov_b32_e32 v20, v132
	v_mov_b32_e32 v21, v133
	v_lshlrev_b32_e32 v23, 16, v20
	v_mul_f32_e32 v24, 0xbfb8aa3b, v23
	v_exp_f32_e32 v24, v24
	v_and_b32_e32 v20, 0xffff0000, v20
	v_div_fixup_f32 v15, v22, v15, 1.0
	v_mul_f32_e32 v16, v16, v15
	v_add_f32_e32 v24, 1.0, v24
	v_div_scale_f32 v25, s[40:41], v24, v24, v23
	v_rcp_f32_e32 v26, v25
	v_mul_f32_e32 v16, v2, v16
	v_lshlrev_b32_e32 v22, 16, v21
	v_mul_f32_e32 v17, v17, v15
	v_fma_f32 v27, -v25, v26, 1.0
	v_fmac_f32_e32 v26, v27, v26
	v_div_scale_f32 v27, vcc, v23, v24, v23
	v_mul_f32_e32 v28, v27, v26
	v_fma_f32 v29, -v25, v28, v27
	v_fmac_f32_e32 v28, v29, v26
	v_fma_f32 v25, -v25, v28, v27
	v_mul_f32_e32 v27, 0xbfb8aa3b, v20
	v_exp_f32_e32 v27, v27
	v_div_fmas_f32 v25, v25, v26, v28
	v_div_fixup_f32 v23, v25, v24, v23
	v_mul_f32_e32 v16, v23, v16
	v_add_f32_e32 v24, 1.0, v27
	v_div_scale_f32 v25, s[40:41], v24, v24, v20
	v_rcp_f32_e32 v26, v25
	v_mul_f32_e32 v17, v3, v17
	v_and_b32_e32 v21, 0xffff0000, v21
	v_mul_f32_e32 v18, v18, v15
	v_fma_f32 v23, -v25, v26, 1.0
	v_fmac_f32_e32 v26, v23, v26
	v_div_scale_f32 v23, vcc, v20, v24, v20
	v_mul_f32_e32 v27, v23, v26
	v_fma_f32 v28, -v25, v27, v23
	v_fmac_f32_e32 v27, v28, v26
	v_fma_f32 v23, -v25, v27, v23
	v_mul_f32_e32 v25, 0xbfb8aa3b, v22
	v_exp_f32_e32 v25, v25
	v_div_fmas_f32 v23, v23, v26, v27
	v_div_fixup_f32 v20, v23, v24, v20
	v_mul_f32_e32 v17, v20, v17
	v_add_f32_e32 v23, 1.0, v25
	v_div_scale_f32 v24, s[40:41], v23, v23, v22
	v_rcp_f32_e32 v25, v24
	v_mul_f32_e32 v15, v19, v15
	v_mul_f32_e32 v18, v4, v18
	v_mul_f32_e32 v15, v5, v15
	v_fma_f32 v20, -v24, v25, 1.0
	v_fmac_f32_e32 v25, v20, v25
	v_div_scale_f32 v20, vcc, v22, v23, v22
	v_mul_f32_e32 v26, v20, v25
	v_fma_f32 v27, -v24, v26, v20
	v_fmac_f32_e32 v26, v27, v25
	v_fma_f32 v20, -v24, v26, v20
	v_mul_f32_e32 v24, 0xbfb8aa3b, v21
	v_exp_f32_e32 v24, v24
	v_div_fmas_f32 v20, v20, v25, v26
	v_div_fixup_f32 v20, v20, v23, v22
	v_mul_f32_e32 v18, v20, v18
	v_add_f32_e32 v22, 1.0, v24
	v_div_scale_f32 v23, s[40:41], v22, v22, v21
	v_rcp_f32_e32 v24, v23
	s_lshl_b64 s[40:41], s[50:51], 13
	s_add_u32 s50, s48, s57
	s_addc_u32 s51, s49, 0
	v_fma_f32 v19, -v23, v24, 1.0
	v_fmac_f32_e32 v24, v19, v24
	v_div_scale_f32 v19, vcc, v21, v22, v21
	v_mul_f32_e32 v20, v19, v24
	v_fma_f32 v25, -v23, v20, v19
	v_fmac_f32_e32 v20, v25, v24
	v_fma_f32 v19, -v23, v20, v19
	v_div_fmas_f32 v19, v19, v24, v20
	v_div_fixup_f32 v19, v19, v22, v21
	v_mul_f32_e32 v15, v19, v15
	v_cvt_pk_bf16_f32 v16, v16, v17
	v_cvt_pk_bf16_f32 v17, v18, v15
	v_lshl_add_u64 v[18:19], v[6:7], 0, s[40:41]
	s_mul_i32 s40, s51, 0x3000
	s_mul_hi_u32 s41, s50, 0x3000
	s_add_i32 s41, s41, s40
	s_mul_i32 s40, s50, 0x3000
	s_add_u32 s40, s90, s40
	s_addc_u32 s41, s91, s41
	s_add_u32 s40, s40, s38
	s_addc_u32 s41, s41, 0
	v_lshl_add_u64 v[20:21], s[40:41], 0, v[78:79]
	v_add_co_u32_e32 v20, vcc, s66, v20
	global_store_dwordx2 v[18:19], v[16:17], off
	s_nop 0
	v_addc_co_u32_e32 v21, vcc, 0, v21, vcc
	ds_read_b128 v[16:19], v14 offset:7216
	s_waitcnt lgkmcnt(0)
	v_mul_f32_e32 v15, v17, v17
	v_mul_f32_e32 v22, v19, v19
	v_fmac_f32_e32 v15, v16, v16
	v_fmac_f32_e32 v22, v18, v18
	v_add_f32_e32 v15, v15, v22
	ds_bpermute_b32 v22, v8, v15
	s_waitcnt lgkmcnt(0)
	v_add_f32_e32 v15, v15, v22
	ds_bpermute_b32 v22, v9, v15
	s_waitcnt lgkmcnt(0)
	v_add_f32_e32 v15, v15, v22
	ds_bpermute_b32 v22, v10, v15
	s_waitcnt lgkmcnt(0)
	v_add_f32_e32 v15, v15, v22
	ds_bpermute_b32 v22, v11, v15
	s_waitcnt lgkmcnt(0)
	v_add_f32_e32 v15, v15, v22
	ds_bpermute_b32 v22, v12, v15
	s_waitcnt lgkmcnt(0)
	v_add_f32_e32 v15, v15, v22
	ds_bpermute_b32 v22, v13, v15
	s_waitcnt lgkmcnt(0)
; #define LAS __attribute__((address_space(3)))
; __device__ __forceinline__ unsigned cvt_pk_bf16(float lo, float hi) { unsigned r; asm volatile("v_cvt_pk_bf16_f32 %0, %1, %2" : "=v"(r) : "v"(lo), "v"(hi)); return r; }
; __device__ __forceinline__ float bflo(unsigned w) { return __uint_as_float(w << 16); }
; __device__ __forceinline__ float bfhi(unsigned w) { return __uint_as_float(w & 0xffff0000u); }
; __device__ __forceinline__ void gc_unit(LAS unsigned char* lds, int unit, const bf16_t* proj, const bf16_t* dSt, const float* gnorm, bf16_t* omix, int tid, int wave, int lane) {
;     ...
;     for (int rr = 0; rr < 8; ++rr) { const int c = 8 * wave + rr; const f32x4 v = *(const LAS f32x4*)(lds + L_OT + c * 1040 + lane * 16);
;         float ss = (v[0] * v[0] + v[1] * v[1]) + (v[2] * v[2] + v[3] * v[3]);
; #pragma unroll
;         for (int o = 1; o < 64; o <<= 1) ss += __shfl_xor(ss, o);
;         const float rs = 1.0f / sqrtf(ss * (1.0f / 256.0f) + EPS);
;         const u32x2 gw2 = *((const u32x2*)(proj + (row0 + c) * PROJ_LD + C_GOUT + h * 256) + lane);
;         const float z0 = bflo(gw2.x), z1 = bfhi(gw2.x), z2 = bflo(gw2.y), z3 = bfhi(gw2.y);
;         const float p0 = v[0] * rs * g[0] * (z0 / (1.0f + __expf(-z0))), p1 = v[1] * rs * g[1] * (z1 / (1.0f + __expf(-z1)));
;         const float p2 = v[2] * rs * g[2] * (z2 / (1.0f + __expf(-z2))), p3 = v[3] * rs * g[3] * (z3 / (1.0f + __expf(-z3)));
;         u32x2 w; w.x = cvt_pk_bf16(p0, p1); w.y = cvt_pk_bf16(p2, p3); *((u32x2*)(omix + (row0 + c) * DM + h * 256) + lane) = w; }
	v_add_f32_e32 v15, v15, v22
	v_fmamk_f32 v15, v15, 0x3b800000, v110
	v_mul_f32_e32 v22, 0x4f800000, v15
	v_cmp_gt_f32_e32 vcc, s65, v15
	s_nop 1
	v_cndmask_b32_e32 v15, v15, v22, vcc
	v_sqrt_f32_e32 v22, v15
	s_nop 0
	v_add_u32_e32 v23, -1, v22
	v_fma_f32 v24, -v23, v22, v15
	v_cmp_ge_f32_e64 s[40:41], 0, v24
	v_add_u32_e32 v24, 1, v22
	s_nop 0
	v_cndmask_b32_e64 v23, v22, v23, s[40:41]
	v_fma_f32 v22, -v24, v22, v15
	v_cmp_lt_f32_e64 s[40:41], 0, v22
	s_nop 1
	v_cndmask_b32_e64 v22, v23, v24, s[40:41]
	v_mul_f32_e32 v23, 0x37800000, v22
	v_cndmask_b32_e32 v22, v22, v23, vcc
	v_cmp_class_f32_e32 vcc, v15, v111
	s_nop 1
	v_cndmask_b32_e32 v15, v22, v15, vcc
	v_div_scale_f32 v22, s[40:41], v15, v15, 1.0
	v_rcp_f32_e32 v23, v22
	s_nop 0
	v_fma_f32 v24, -v22, v23, 1.0
	v_fmac_f32_e32 v23, v24, v23
	v_div_scale_f32 v24, vcc, 1.0, v15, 1.0
	v_mul_f32_e32 v25, v24, v23
	v_fma_f32 v26, -v22, v25, v24
	v_fmac_f32_e32 v25, v26, v23
	v_fma_f32 v22, -v22, v25, v24
	v_div_fmas_f32 v22, v22, v23, v25
	v_mov_b32_e32 v20, v134
	v_mov_b32_e32 v21, v135
	v_lshlrev_b32_e32 v23, 16, v20
	v_mul_f32_e32 v24, 0xbfb8aa3b, v23
	v_exp_f32_e32 v24, v24
	v_and_b32_e32 v20, 0xffff0000, v20
	v_div_fixup_f32 v15, v22, v15, 1.0
	v_mul_f32_e32 v16, v16, v15
	v_add_f32_e32 v24, 1.0, v24
	v_div_scale_f32 v25, s[40:41], v24, v24, v23
	v_rcp_f32_e32 v26, v25
	v_mul_f32_e32 v16, v2, v16
	v_lshlrev_b32_e32 v22, 16, v21
	v_mul_f32_e32 v17, v17, v15
	v_fma_f32 v27, -v25, v26, 1.0
	v_fmac_f32_e32 v26, v27, v26
	v_div_scale_f32 v27, vcc, v23, v24, v23
	v_mul_f32_e32 v28, v27, v26
	v_fma_f32 v29, -v25, v28, v27
	v_fmac_f32_e32 v28, v29, v26
	v_fma_f32 v25, -v25, v28, v27
	v_mul_f32_e32 v27, 0xbfb8aa3b, v20
	v_exp_f32_e32 v27, v27
	v_div_fmas_f32 v25, v25, v26, v28
	v_div_fixup_f32 v23, v25, v24, v23
	v_mul_f32_e32 v16, v23, v16
	v_add_f32_e32 v24, 1.0, v27
	v_div_scale_f32 v25, s[40:41], v24, v24, v20
	v_rcp_f32_e32 v26, v25
	v_mul_f32_e32 v17, v3, v17
	v_and_b32_e32 v21, 0xffff0000, v21
	v_mul_f32_e32 v18, v18, v15
	v_fma_f32 v23, -v25, v26, 1.0
	v_fmac_f32_e32 v26, v23, v26
	v_div_scale_f32 v23, vcc, v20, v24, v20
	v_mul_f32_e32 v27, v23, v26
	v_fma_f32 v28, -v25, v27, v23
	v_fmac_f32_e32 v27, v28, v26
	v_fma_f32 v23, -v25, v27, v23
	v_mul_f32_e32 v25, 0xbfb8aa3b, v22
	v_exp_f32_e32 v25, v25
	v_div_fmas_f32 v23, v23, v26, v27
	v_div_fixup_f32 v20, v23, v24, v20
	v_mul_f32_e32 v17, v20, v17
	v_add_f32_e32 v23, 1.0, v25
	v_div_scale_f32 v24, s[40:41], v23, v23, v22
	v_rcp_f32_e32 v25, v24
	v_mul_f32_e32 v15, v19, v15
	v_mul_f32_e32 v18, v4, v18
	v_mul_f32_e32 v15, v5, v15
	v_fma_f32 v20, -v24, v25, 1.0
	v_fmac_f32_e32 v25, v20, v25
	v_div_scale_f32 v20, vcc, v22, v23, v22
	v_mul_f32_e32 v26, v20, v25
	v_fma_f32 v27, -v24, v26, v20
	v_fmac_f32_e32 v26, v27, v25
	v_fma_f32 v20, -v24, v26, v20
	v_mul_f32_e32 v24, 0xbfb8aa3b, v21
	v_exp_f32_e32 v24, v24
	v_div_fmas_f32 v20, v20, v25, v26
	v_div_fixup_f32 v20, v20, v23, v22
	v_mul_f32_e32 v18, v20, v18
	v_add_f32_e32 v22, 1.0, v24
	v_div_scale_f32 v23, s[40:41], v22, v22, v21
	v_rcp_f32_e32 v24, v23
	s_lshl_b64 s[40:41], s[50:51], 13
	s_add_u32 s50, s48, s58
	s_addc_u32 s51, s49, 0
	v_fma_f32 v19, -v23, v24, 1.0
	v_fmac_f32_e32 v24, v19, v24
	v_div_scale_f32 v19, vcc, v21, v22, v21
	v_mul_f32_e32 v20, v19, v24
	v_fma_f32 v25, -v23, v20, v19
	v_fmac_f32_e32 v20, v25, v24
	v_fma_f32 v19, -v23, v20, v19
	v_div_fmas_f32 v19, v19, v24, v20
	v_div_fixup_f32 v19, v19, v22, v21
	v_mul_f32_e32 v15, v19, v15
	v_cvt_pk_bf16_f32 v16, v16, v17
	v_cvt_pk_bf16_f32 v17, v18, v15
	v_lshl_add_u64 v[18:19], v[6:7], 0, s[40:41]
	s_mul_i32 s40, s51, 0x3000
	s_mul_hi_u32 s41, s50, 0x3000
	s_add_i32 s41, s41, s40
	s_mul_i32 s40, s50, 0x3000
	s_add_u32 s40, s90, s40
	s_addc_u32 s41, s91, s41
	s_add_u32 s40, s40, s38
	s_addc_u32 s41, s41, 0
	v_lshl_add_u64 v[20:21], s[40:41], 0, v[78:79]
	v_add_co_u32_e32 v20, vcc, s66, v20
	global_store_dwordx2 v[18:19], v[16:17], off
	s_nop 0
	v_addc_co_u32_e32 v21, vcc, 0, v21, vcc
	ds_read_b128 v[16:19], v14 offset:8256
	s_waitcnt lgkmcnt(0)
	v_mul_f32_e32 v15, v17, v17
	v_mul_f32_e32 v22, v19, v19
	v_fmac_f32_e32 v15, v16, v16
	v_fmac_f32_e32 v22, v18, v18
	v_add_f32_e32 v15, v15, v22
	ds_bpermute_b32 v22, v8, v15
	s_waitcnt lgkmcnt(0)
	v_add_f32_e32 v15, v15, v22
	ds_bpermute_b32 v22, v9, v15
	s_waitcnt lgkmcnt(0)
	v_add_f32_e32 v15, v15, v22
	ds_bpermute_b32 v22, v10, v15
	s_waitcnt lgkmcnt(0)
	v_add_f32_e32 v15, v15, v22
	ds_bpermute_b32 v22, v11, v15
	s_waitcnt lgkmcnt(0)
	v_add_f32_e32 v15, v15, v22
	ds_bpermute_b32 v22, v12, v15
	s_waitcnt lgkmcnt(0)
	v_add_f32_e32 v15, v15, v22
	ds_bpermute_b32 v22, v13, v15
	s_waitcnt lgkmcnt(0)
; #define LAS __attribute__((address_space(3)))
; __device__ __forceinline__ unsigned cvt_pk_bf16(float lo, float hi) { unsigned r; asm volatile("v_cvt_pk_bf16_f32 %0, %1, %2" : "=v"(r) : "v"(lo), "v"(hi)); return r; }
; __device__ __forceinline__ float bflo(unsigned w) { return __uint_as_float(w << 16); }
; __device__ __forceinline__ float bfhi(unsigned w) { return __uint_as_float(w & 0xffff0000u); }
; __device__ __forceinline__ void gc_unit(LAS unsigned char* lds, int unit, const bf16_t* proj, const bf16_t* dSt, const float* gnorm, bf16_t* omix, int tid, int wave, int lane) {
;     ...
;     for (int rr = 0; rr < 8; ++rr) { const int c = 8 * wave + rr; const f32x4 v = *(const LAS f32x4*)(lds + L_OT + c * 1040 + lane * 16);
;         float ss = (v[0] * v[0] + v[1] * v[1]) + (v[2] * v[2] + v[3] * v[3]);
; #pragma unroll
;         for (int o = 1; o < 64; o <<= 1) ss += __shfl_xor(ss, o);
;         const float rs = 1.0f / sqrtf(ss * (1.0f / 256.0f) + EPS);
;         const u32x2 gw2 = *((const u32x2*)(proj + (row0 + c) * PROJ_LD + C_GOUT + h * 256) + lane);
;         const float z0 = bflo(gw2.x), z1 = bfhi(gw2.x), z2 = bflo(gw2.y), z3 = bfhi(gw2.y);
;         const float p0 = v[0] * rs * g[0] * (z0 / (1.0f + __expf(-z0))), p1 = v[1] * rs * g[1] * (z1 / (1.0f + __expf(-z1)));
;         const float p2 = v[2] * rs * g[2] * (z2 / (1.0f + __expf(-z2))), p3 = v[3] * rs * g[3] * (z3 / (1.0f + __expf(-z3)));
;         u32x2 w; w.x = cvt_pk_bf16(p0, p1); w.y = cvt_pk_bf16(p2, p3); *((u32x2*)(omix + (row0 + c) * DM + h * 256) + lane) = w; }
	v_add_f32_e32 v15, v15, v22
	v_fmamk_f32 v15, v15, 0x3b800000, v110
	v_mul_f32_e32 v22, 0x4f800000, v15
	v_cmp_gt_f32_e32 vcc, s65, v15
	s_nop 1
	v_cndmask_b32_e32 v15, v15, v22, vcc
	v_sqrt_f32_e32 v22, v15
	s_nop 0
	v_add_u32_e32 v23, -1, v22
	v_fma_f32 v24, -v23, v22, v15
	v_cmp_ge_f32_e64 s[40:41], 0, v24
	v_add_u32_e32 v24, 1, v22
	s_nop 0
	v_cndmask_b32_e64 v23, v22, v23, s[40:41]
	v_fma_f32 v22, -v24, v22, v15
	v_cmp_lt_f32_e64 s[40:41], 0, v22
	s_nop 1
	v_cndmask_b32_e64 v22, v23, v24, s[40:41]
	v_mul_f32_e32 v23, 0x37800000, v22
	v_cndmask_b32_e32 v22, v22, v23, vcc
	v_cmp_class_f32_e32 vcc, v15, v111
	s_nop 1
	v_cndmask_b32_e32 v15, v22, v15, vcc
	v_div_scale_f32 v22, s[40:41], v15, v15, 1.0
	v_rcp_f32_e32 v23, v22
	s_nop 0
	v_fma_f32 v24, -v22, v23, 1.0
	v_fmac_f32_e32 v23, v24, v23
	v_div_scale_f32 v24, vcc, 1.0, v15, 1.0
	v_mul_f32_e32 v25, v24, v23
	v_fma_f32 v26, -v22, v25, v24
	v_fmac_f32_e32 v25, v26, v23
	v_fma_f32 v22, -v22, v25, v24
	v_div_fmas_f32 v22, v22, v23, v25
	v_mov_b32_e32 v20, v136
	v_mov_b32_e32 v21, v137
	v_lshlrev_b32_e32 v23, 16, v20
	v_mul_f32_e32 v24, 0xbfb8aa3b, v23
	v_exp_f32_e32 v24, v24
	v_and_b32_e32 v20, 0xffff0000, v20
	v_div_fixup_f32 v15, v22, v15, 1.0
	v_mul_f32_e32 v16, v16, v15
	v_add_f32_e32 v24, 1.0, v24
	v_div_scale_f32 v25, s[40:41], v24, v24, v23
	v_rcp_f32_e32 v26, v25
	v_mul_f32_e32 v16, v2, v16
	v_lshlrev_b32_e32 v22, 16, v21
	v_mul_f32_e32 v17, v17, v15
	v_fma_f32 v27, -v25, v26, 1.0
	v_fmac_f32_e32 v26, v27, v26
	v_div_scale_f32 v27, vcc, v23, v24, v23
	v_mul_f32_e32 v28, v27, v26
	v_fma_f32 v29, -v25, v28, v27
	v_fmac_f32_e32 v28, v29, v26
	v_fma_f32 v25, -v25, v28, v27
	v_mul_f32_e32 v27, 0xbfb8aa3b, v20
	v_exp_f32_e32 v27, v27
	v_div_fmas_f32 v25, v25, v26, v28
	v_div_fixup_f32 v23, v25, v24, v23
	v_mul_f32_e32 v16, v23, v16
	v_add_f32_e32 v24, 1.0, v27
	v_div_scale_f32 v25, s[40:41], v24, v24, v20
	v_rcp_f32_e32 v26, v25
	v_mul_f32_e32 v17, v3, v17
	v_and_b32_e32 v21, 0xffff0000, v21
	v_mul_f32_e32 v18, v18, v15
	v_fma_f32 v23, -v25, v26, 1.0
	v_fmac_f32_e32 v26, v23, v26
	v_div_scale_f32 v23, vcc, v20, v24, v20
	v_mul_f32_e32 v27, v23, v26
	v_fma_f32 v28, -v25, v27, v23
	v_fmac_f32_e32 v27, v28, v26
	v_fma_f32 v23, -v25, v27, v23
	v_mul_f32_e32 v25, 0xbfb8aa3b, v22
	v_exp_f32_e32 v25, v25
	v_div_fmas_f32 v23, v23, v26, v27
	v_div_fixup_f32 v20, v23, v24, v20
	v_mul_f32_e32 v17, v20, v17
	v_add_f32_e32 v23, 1.0, v25
	v_div_scale_f32 v24, s[40:41], v23, v23, v22
	v_rcp_f32_e32 v25, v24
	v_mul_f32_e32 v15, v19, v15
	v_mul_f32_e32 v18, v4, v18
	v_mul_f32_e32 v15, v5, v15
	v_fma_f32 v20, -v24, v25, 1.0
	v_fmac_f32_e32 v25, v20, v25
	v_div_scale_f32 v20, vcc, v22, v23, v22
	v_mul_f32_e32 v26, v20, v25
	v_fma_f32 v27, -v24, v26, v20
	v_fmac_f32_e32 v26, v27, v25
	v_fma_f32 v20, -v24, v26, v20
	v_mul_f32_e32 v24, 0xbfb8aa3b, v21
	v_exp_f32_e32 v24, v24
	v_div_fmas_f32 v20, v20, v25, v26
	v_div_fixup_f32 v20, v20, v23, v22
	v_mul_f32_e32 v18, v20, v18
	v_add_f32_e32 v22, 1.0, v24
	v_div_scale_f32 v23, s[40:41], v22, v22, v21
	v_rcp_f32_e32 v24, v23
	s_lshl_b64 s[40:41], s[50:51], 13
	s_add_u32 s50, s48, s59
	s_addc_u32 s51, s49, 0
	v_fma_f32 v19, -v23, v24, 1.0
	v_fmac_f32_e32 v24, v19, v24
	v_div_scale_f32 v19, vcc, v21, v22, v21
	v_mul_f32_e32 v20, v19, v24
	v_fma_f32 v25, -v23, v20, v19
	v_fmac_f32_e32 v20, v25, v24
	v_fma_f32 v19, -v23, v20, v19
	v_div_fmas_f32 v19, v19, v24, v20
	v_div_fixup_f32 v19, v19, v22, v21
	v_mul_f32_e32 v15, v19, v15
	v_cvt_pk_bf16_f32 v16, v16, v17
	v_cvt_pk_bf16_f32 v17, v18, v15
	v_lshl_add_u64 v[18:19], v[6:7], 0, s[40:41]
	s_mul_i32 s40, s51, 0x3000
	s_mul_hi_u32 s41, s50, 0x3000
	s_add_i32 s41, s41, s40
	s_mul_i32 s40, s50, 0x3000
	s_add_u32 s40, s90, s40
	s_addc_u32 s41, s91, s41
	s_add_u32 s40, s40, s38
	s_addc_u32 s41, s41, 0
	v_lshl_add_u64 v[20:21], s[40:41], 0, v[78:79]
	v_add_co_u32_e32 v20, vcc, s66, v20
	global_store_dwordx2 v[18:19], v[16:17], off
	s_nop 0
	v_addc_co_u32_e32 v21, vcc, 0, v21, vcc
	ds_read_b128 v[16:19], v14 offset:9296
	s_waitcnt lgkmcnt(0)
	v_mul_f32_e32 v15, v17, v17
	v_mul_f32_e32 v22, v19, v19
	v_fmac_f32_e32 v15, v16, v16
	v_fmac_f32_e32 v22, v18, v18
	v_add_f32_e32 v15, v15, v22
	ds_bpermute_b32 v22, v8, v15
	s_waitcnt lgkmcnt(0)
	v_add_f32_e32 v15, v15, v22
	ds_bpermute_b32 v22, v9, v15
	s_waitcnt lgkmcnt(0)
	v_add_f32_e32 v15, v15, v22
	ds_bpermute_b32 v22, v10, v15
	s_waitcnt lgkmcnt(0)
	v_add_f32_e32 v15, v15, v22
	ds_bpermute_b32 v22, v11, v15
	s_waitcnt lgkmcnt(0)
	v_add_f32_e32 v15, v15, v22
	ds_bpermute_b32 v22, v12, v15
	s_waitcnt lgkmcnt(0)
	v_add_f32_e32 v15, v15, v22
	ds_bpermute_b32 v22, v13, v15
	s_waitcnt lgkmcnt(0)
; #define LAS __attribute__((address_space(3)))
; __device__ __forceinline__ unsigned cvt_pk_bf16(float lo, float hi) { unsigned r; asm volatile("v_cvt_pk_bf16_f32 %0, %1, %2" : "=v"(r) : "v"(lo), "v"(hi)); return r; }
; __device__ __forceinline__ float bflo(unsigned w) { return __uint_as_float(w << 16); }
; __device__ __forceinline__ float bfhi(unsigned w) { return __uint_as_float(w & 0xffff0000u); }
; __device__ __forceinline__ void gc_unit(LAS unsigned char* lds, int unit, const bf16_t* proj, const bf16_t* dSt, const float* gnorm, bf16_t* omix, int tid, int wave, int lane) {
;     ...
;     for (int rr = 0; rr < 8; ++rr) { const int c = 8 * wave + rr; const f32x4 v = *(const LAS f32x4*)(lds + L_OT + c * 1040 + lane * 16);
;         float ss = (v[0] * v[0] + v[1] * v[1]) + (v[2] * v[2] + v[3] * v[3]);
; #pragma unroll
;         for (int o = 1; o < 64; o <<= 1) ss += __shfl_xor(ss, o);
;         const float rs = 1.0f / sqrtf(ss * (1.0f / 256.0f) + EPS);
;         const u32x2 gw2 = *((const u32x2*)(proj + (row0 + c) * PROJ_LD + C_GOUT + h * 256) + lane);
;         const float z0 = bflo(gw2.x), z1 = bfhi(gw2.x), z2 = bflo(gw2.y), z3 = bfhi(gw2.y);
;         const float p0 = v[0] * rs * g[0] * (z0 / (1.0f + __expf(-z0))), p1 = v[1] * rs * g[1] * (z1 / (1.0f + __expf(-z1)));
;         const float p2 = v[2] * rs * g[2] * (z2 / (1.0f + __expf(-z2))), p3 = v[3] * rs * g[3] * (z3 / (1.0f + __expf(-z3)));
;         u32x2 w; w.x = cvt_pk_bf16(p0, p1); w.y = cvt_pk_bf16(p2, p3); *((u32x2*)(omix + (row0 + c) * DM + h * 256) + lane) = w; }
	v_add_f32_e32 v15, v15, v22
	v_fmamk_f32 v15, v15, 0x3b800000, v110
	v_mul_f32_e32 v22, 0x4f800000, v15
	v_cmp_gt_f32_e32 vcc, s65, v15
	s_nop 1
	v_cndmask_b32_e32 v15, v15, v22, vcc
	v_sqrt_f32_e32 v22, v15
	s_nop 0
	v_add_u32_e32 v23, -1, v22
	v_fma_f32 v24, -v23, v22, v15
	v_cmp_ge_f32_e64 s[40:41], 0, v24
	v_add_u32_e32 v24, 1, v22
	s_nop 0
	v_cndmask_b32_e64 v23, v22, v23, s[40:41]
	v_fma_f32 v22, -v24, v22, v15
	v_cmp_lt_f32_e64 s[40:41], 0, v22
	s_nop 1
	v_cndmask_b32_e64 v22, v23, v24, s[40:41]
	v_mul_f32_e32 v23, 0x37800000, v22
	v_cndmask_b32_e32 v22, v22, v23, vcc
	v_cmp_class_f32_e32 vcc, v15, v111
	s_nop 1
	v_cndmask_b32_e32 v15, v22, v15, vcc
	v_div_scale_f32 v22, s[40:41], v15, v15, 1.0
	v_rcp_f32_e32 v23, v22
	s_nop 0
	v_fma_f32 v24, -v22, v23, 1.0
	v_fmac_f32_e32 v23, v24, v23
	v_div_scale_f32 v24, vcc, 1.0, v15, 1.0
	v_mul_f32_e32 v25, v24, v23
	v_fma_f32 v26, -v22, v25, v24
	v_fmac_f32_e32 v25, v26, v23
	v_fma_f32 v22, -v22, v25, v24
	v_div_fmas_f32 v22, v22, v23, v25
	v_mov_b32_e32 v20, v138
	v_mov_b32_e32 v21, v139
	v_lshlrev_b32_e32 v23, 16, v20
	v_mul_f32_e32 v24, 0xbfb8aa3b, v23
	v_exp_f32_e32 v24, v24
	v_and_b32_e32 v20, 0xffff0000, v20
	v_div_fixup_f32 v15, v22, v15, 1.0
	v_mul_f32_e32 v16, v16, v15
	v_add_f32_e32 v24, 1.0, v24
	v_div_scale_f32 v25, s[40:41], v24, v24, v23
	v_rcp_f32_e32 v26, v25
	v_mul_f32_e32 v16, v2, v16
	v_lshlrev_b32_e32 v22, 16, v21
	v_mul_f32_e32 v17, v17, v15
	v_fma_f32 v27, -v25, v26, 1.0
	v_fmac_f32_e32 v26, v27, v26
	v_div_scale_f32 v27, vcc, v23, v24, v23
	v_mul_f32_e32 v28, v27, v26
	v_fma_f32 v29, -v25, v28, v27
	v_fmac_f32_e32 v28, v29, v26
	v_fma_f32 v25, -v25, v28, v27
	v_mul_f32_e32 v27, 0xbfb8aa3b, v20
	v_exp_f32_e32 v27, v27
	v_div_fmas_f32 v25, v25, v26, v28
	v_div_fixup_f32 v23, v25, v24, v23
	v_mul_f32_e32 v16, v23, v16
	v_add_f32_e32 v24, 1.0, v27
	v_div_scale_f32 v25, s[40:41], v24, v24, v20
	v_rcp_f32_e32 v26, v25
	v_mul_f32_e32 v17, v3, v17
	v_and_b32_e32 v21, 0xffff0000, v21
	v_mul_f32_e32 v18, v18, v15
	v_fma_f32 v23, -v25, v26, 1.0
	v_fmac_f32_e32 v26, v23, v26
	v_div_scale_f32 v23, vcc, v20, v24, v20
	v_mul_f32_e32 v27, v23, v26
	v_fma_f32 v28, -v25, v27, v23
	v_fmac_f32_e32 v27, v28, v26
	v_fma_f32 v23, -v25, v27, v23
	v_mul_f32_e32 v25, 0xbfb8aa3b, v22
	v_exp_f32_e32 v25, v25
	v_div_fmas_f32 v23, v23, v26, v27
	v_div_fixup_f32 v20, v23, v24, v20
	v_mul_f32_e32 v17, v20, v17
	v_add_f32_e32 v23, 1.0, v25
	v_div_scale_f32 v24, s[40:41], v23, v23, v22
	v_rcp_f32_e32 v25, v24
	v_mul_f32_e32 v15, v19, v15
	v_mul_f32_e32 v18, v4, v18
	v_mul_f32_e32 v15, v5, v15
	v_fma_f32 v20, -v24, v25, 1.0
	v_fmac_f32_e32 v25, v20, v25
	v_div_scale_f32 v20, vcc, v22, v23, v22
	v_mul_f32_e32 v26, v20, v25
	v_fma_f32 v27, -v24, v26, v20
	v_fmac_f32_e32 v26, v27, v25
	v_fma_f32 v20, -v24, v26, v20
	v_mul_f32_e32 v24, 0xbfb8aa3b, v21
	v_exp_f32_e32 v24, v24
	v_div_fmas_f32 v20, v20, v25, v26
	v_div_fixup_f32 v20, v20, v23, v22
	v_mul_f32_e32 v18, v20, v18
	v_add_f32_e32 v22, 1.0, v24
	v_div_scale_f32 v23, s[40:41], v22, v22, v21
	v_rcp_f32_e32 v24, v23
	s_lshl_b64 s[40:41], s[50:51], 13
	s_add_u32 s48, s48, s60
	s_addc_u32 s49, s49, 0
	v_fma_f32 v19, -v23, v24, 1.0
	v_fmac_f32_e32 v24, v19, v24
	v_div_scale_f32 v19, vcc, v21, v22, v21
	v_mul_f32_e32 v20, v19, v24
	v_fma_f32 v25, -v23, v20, v19
	v_fmac_f32_e32 v20, v25, v24
	v_fma_f32 v19, -v23, v20, v19
	v_div_fmas_f32 v19, v19, v24, v20
	v_div_fixup_f32 v19, v19, v22, v21
	v_mul_f32_e32 v15, v19, v15
	v_cvt_pk_bf16_f32 v16, v16, v17
	v_cvt_pk_bf16_f32 v17, v18, v15
	v_lshl_add_u64 v[18:19], v[6:7], 0, s[40:41]
	s_mul_i32 s40, s49, 0x3000
	s_mul_hi_u32 s41, s48, 0x3000
	s_add_i32 s41, s41, s40
	s_mul_i32 s40, s48, 0x3000
	s_add_u32 s40, s90, s40
	s_addc_u32 s41, s91, s41
	s_add_u32 s40, s40, s38
	s_addc_u32 s41, s41, 0
	global_store_dwordx2 v[18:19], v[16:17], off
	v_lshl_add_u64 v[18:19], s[40:41], 0, v[78:79]
	v_add_co_u32_e32 v18, vcc, s66, v18
	ds_read_b128 v[14:17], v14 offset:10336
	s_nop 0
	v_addc_co_u32_e32 v19, vcc, 0, v19, vcc
	s_add_i32 s94, s94, s88
	s_waitcnt lgkmcnt(0)
; #define LAS __attribute__((address_space(3)))
; __device__ __forceinline__ unsigned cvt_pk_bf16(float lo, float hi) { unsigned r; asm volatile("v_cvt_pk_bf16_f32 %0, %1, %2" : "=v"(r) : "v"(lo), "v"(hi)); return r; }
; __device__ __forceinline__ float bflo(unsigned w) { return __uint_as_float(w << 16); }
; __device__ __forceinline__ float bfhi(unsigned w) { return __uint_as_float(w & 0xffff0000u); }
; __device__ __forceinline__ void gc_unit(LAS unsigned char* lds, int unit, const bf16_t* proj, const bf16_t* dSt, const float* gnorm, bf16_t* omix, int tid, int wave, int lane) {
;     ...
;     for (int rr = 0; rr < 8; ++rr) { const int c = 8 * wave + rr; const f32x4 v = *(const LAS f32x4*)(lds + L_OT + c * 1040 + lane * 16);
;         float ss = (v[0] * v[0] + v[1] * v[1]) + (v[2] * v[2] + v[3] * v[3]);
; #pragma unroll
;         for (int o = 1; o < 64; o <<= 1) ss += __shfl_xor(ss, o);
;         const float rs = 1.0f / sqrtf(ss * (1.0f / 256.0f) + EPS);
;         const u32x2 gw2 = *((const u32x2*)(proj + (row0 + c) * PROJ_LD + C_GOUT + h * 256) + lane);
;         const float z0 = bflo(gw2.x), z1 = bfhi(gw2.x), z2 = bflo(gw2.y), z3 = bfhi(gw2.y);
;         const float p0 = v[0] * rs * g[0] * (z0 / (1.0f + __expf(-z0))), p1 = v[1] * rs * g[1] * (z1 / (1.0f + __expf(-z1)));
;         const float p2 = v[2] * rs * g[2] * (z2 / (1.0f + __expf(-z2))), p3 = v[3] * rs * g[3] * (z3 / (1.0f + __expf(-z3)));
;         u32x2 w; w.x = cvt_pk_bf16(p0, p1); w.y = cvt_pk_bf16(p2, p3); *((u32x2*)(omix + (row0 + c) * DM + h * 256) + lane) = w; }
	v_mul_f32_e32 v20, v15, v15
	v_mul_f32_e32 v21, v17, v17
	v_fmac_f32_e32 v20, v14, v14
	v_fmac_f32_e32 v21, v16, v16
	v_add_f32_e32 v20, v20, v21
	ds_bpermute_b32 v8, v8, v20
	s_add_i32 s61, s61, s62
	s_waitcnt lgkmcnt(0)
	v_add_f32_e32 v8, v20, v8
	ds_bpermute_b32 v9, v9, v8
	s_waitcnt lgkmcnt(0)
	v_add_f32_e32 v8, v8, v9
	ds_bpermute_b32 v9, v10, v8
	s_waitcnt lgkmcnt(0)
	v_add_f32_e32 v8, v8, v9
	ds_bpermute_b32 v9, v11, v8
	s_waitcnt lgkmcnt(0)
	v_add_f32_e32 v8, v8, v9
	ds_bpermute_b32 v9, v12, v8
	s_waitcnt lgkmcnt(0)
	v_add_f32_e32 v8, v8, v9
	ds_bpermute_b32 v9, v13, v8
	s_waitcnt lgkmcnt(0)
	v_add_f32_e32 v8, v8, v9
	v_fmamk_f32 v8, v8, 0x3b800000, v110
	v_mul_f32_e32 v9, 0x4f800000, v8
	v_cmp_gt_f32_e32 vcc, s65, v8
	s_nop 1
	v_cndmask_b32_e32 v8, v8, v9, vcc
	v_sqrt_f32_e32 v9, v8
	s_nop 0
	v_add_u32_e32 v10, -1, v9
	v_fma_f32 v11, -v10, v9, v8
	v_cmp_ge_f32_e64 s[40:41], 0, v11
	v_add_u32_e32 v11, 1, v9
	s_nop 0
	v_cndmask_b32_e64 v10, v9, v10, s[40:41]
	v_fma_f32 v9, -v11, v9, v8
	v_cmp_lt_f32_e64 s[40:41], 0, v9
	s_nop 1
	v_cndmask_b32_e64 v9, v10, v11, s[40:41]
	v_mul_f32_e32 v10, 0x37800000, v9
	v_cndmask_b32_e32 v9, v9, v10, vcc
	v_cmp_class_f32_e32 vcc, v8, v111
	s_nop 1
	v_cndmask_b32_e32 v8, v9, v8, vcc
	v_div_scale_f32 v9, s[40:41], v8, v8, 1.0
	v_rcp_f32_e32 v10, v9
	s_nop 0
	v_fma_f32 v11, -v9, v10, 1.0
	v_fmac_f32_e32 v10, v11, v10
	v_div_scale_f32 v11, vcc, 1.0, v8, 1.0
	v_mul_f32_e32 v12, v11, v10
	v_fma_f32 v13, -v9, v12, v11
	v_fmac_f32_e32 v12, v13, v10
	v_fma_f32 v9, -v9, v12, v11
	v_div_fmas_f32 v9, v9, v10, v12
	v_mov_b32_e32 v18, v140
	v_mov_b32_e32 v19, v141
	v_lshlrev_b32_e32 v10, 16, v18
	v_mul_f32_e32 v11, 0xbfb8aa3b, v10
	v_exp_f32_e32 v11, v11
	v_div_fixup_f32 v8, v9, v8, 1.0
	v_and_b32_e32 v9, 0xffff0000, v18
	v_mul_f32_e32 v14, v14, v8
	v_add_f32_e32 v11, 1.0, v11
	v_div_scale_f32 v13, s[40:41], v11, v11, v10
	v_rcp_f32_e32 v18, v13
	v_mul_f32_e32 v2, v2, v14
	v_lshlrev_b32_e32 v12, 16, v19
	v_and_b32_e32 v19, 0xffff0000, v19
	v_fma_f32 v14, -v13, v18, 1.0
	v_fmac_f32_e32 v18, v14, v18
	v_div_scale_f32 v14, vcc, v10, v11, v10
	v_mul_f32_e32 v20, v14, v18
	v_fma_f32 v21, -v13, v20, v14
	v_fmac_f32_e32 v20, v21, v18
	v_fma_f32 v13, -v13, v20, v14
	v_mul_f32_e32 v14, 0xbfb8aa3b, v9
	v_exp_f32_e32 v14, v14
	v_div_fmas_f32 v13, v13, v18, v20
	v_div_fixup_f32 v10, v13, v11, v10
	v_mul_f32_e32 v2, v10, v2
	v_add_f32_e32 v11, 1.0, v14
	v_div_scale_f32 v13, s[40:41], v11, v11, v9
	v_rcp_f32_e32 v14, v13
	v_mul_f32_e32 v10, v15, v8
	v_mul_f32_e32 v3, v3, v10
	v_fma_f32 v10, -v13, v14, 1.0
	v_fmac_f32_e32 v14, v10, v14
	v_div_scale_f32 v10, vcc, v9, v11, v9
	v_mul_f32_e32 v15, v10, v14
	v_fma_f32 v18, -v13, v15, v10
	v_fmac_f32_e32 v15, v18, v14
	v_fma_f32 v10, -v13, v15, v10
	v_mul_f32_e32 v13, 0xbfb8aa3b, v12
	v_exp_f32_e32 v13, v13
	v_div_fmas_f32 v10, v10, v14, v15
	v_div_fixup_f32 v9, v10, v11, v9
	v_mul_f32_e32 v3, v9, v3
	v_add_f32_e32 v10, 1.0, v13
	v_div_scale_f32 v11, s[40:41], v10, v10, v12
	v_rcp_f32_e32 v13, v11
	v_mul_f32_e32 v9, v16, v8
	v_mul_f32_e32 v4, v4, v9
	v_mul_f32_e32 v8, v17, v8
	v_fma_f32 v9, -v11, v13, 1.0
	v_fmac_f32_e32 v13, v9, v13
	v_div_scale_f32 v9, vcc, v12, v10, v12
	v_mul_f32_e32 v14, v9, v13
	v_fma_f32 v15, -v11, v14, v9
	v_fmac_f32_e32 v14, v15, v13
	v_fma_f32 v9, -v11, v14, v9
	v_mul_f32_e32 v11, 0xbfb8aa3b, v19
	v_exp_f32_e32 v11, v11
	v_div_fmas_f32 v9, v9, v13, v14
	v_div_fixup_f32 v9, v9, v10, v12
	v_mul_f32_e32 v5, v5, v8
	v_add_f32_e32 v10, 1.0, v11
	v_div_scale_f32 v11, s[40:41], v10, v10, v19
	v_rcp_f32_e32 v12, v11
	v_mul_f32_e32 v4, v9, v4
	s_lshl_b64 s[40:41], s[48:49], 13
	v_cvt_pk_bf16_f32 v2, v2, v3
	v_fma_f32 v8, -v11, v12, 1.0
	v_fmac_f32_e32 v12, v8, v12
	v_div_scale_f32 v8, vcc, v19, v10, v19
	v_mul_f32_e32 v9, v8, v12
	v_fma_f32 v13, -v11, v9, v8
	v_fmac_f32_e32 v9, v13, v12
	v_fma_f32 v8, -v11, v9, v8
	v_div_fmas_f32 v8, v8, v12, v9
	v_div_fixup_f32 v8, v8, v10, v19
	v_mul_f32_e32 v5, v8, v5
	v_cvt_pk_bf16_f32 v3, v4, v5
	v_lshl_add_u64 v[4:5], v[6:7], 0, s[40:41]
	s_cmpk_lt_i32 s94, 0x800
	global_store_dwordx2 v[4:5], v[2:3], off
	s_barrier
	s_cbranch_scc0 .LBB0_1022

; template <class Epi, class Sched, class Ptrs, bool ALIGN_EPI, bool I8 = false>
; __device__ __forceinline__ void gemm_phase(LAS unsigned char* lds, const Ptrs& P, const Sched& S, const Epi& E) {
;     ...
;         for (int a = 0; a < 2; ++a)
; #pragma unroll
;             for (int b = 0; b < 2; ++b)
; #pragma unroll
;                 for (int m = 0; m < 4; ++m)
; #pragma unroll
;                     for (int n = 0; n < 2; ++n) acc[a][b][m][n] = acc_t{};
;         cur = nxt; cA = nA; cB = nB; ++ui;
;     __device__ __forceinline__ void operator()(const i32x4 (&acc)[2][2][4][2], const Unit& u, int wr, int wc, int fr, int fq) const {
;     ...
;         f32x4 cs[2][2];
; #pragma unroll
;         for (int bj = 0; bj < 2; ++bj) { cs[bj][0] = *(const f32x4*)(cscale + col0 + bj * HALF); cs[bj][1] = *(const f32x4*)(cscale + col0 + bj * HALF + 4); }
;         float rsv[2][4];
; #pragma unroll
;         for (int ai = 0; ai < 2; ++ai)
; #pragma unroll
;             for (int m = 0; m < 4; ++m) rsv[ai][m] = rowq[row0 + ai * HALF + m * 16];
.LBB0_1477:
	s_ashr_i32 s29, s28, 31
	s_lshl_b64 s[30:31], s[28:29], 20
	s_add_u32 s30, s0, s30
	s_addc_u32 s31, s1, s31
	s_and_b64 s[34:35], s[4:5], exec
	s_cselect_b32 s29, s31, s39
	s_cselect_b32 s57, s30, s38
	s_ashr_i32 s27, s26, 31
	s_lshl_b64 s[34:35], s[26:27], 20
	s_add_u32 s34, s44, s34
	s_addc_u32 s35, s45, s35
	s_and_b64 s[42:43], s[4:5], exec
	s_cselect_b32 s27, s35, s41
	s_cselect_b32 s58, s34, s40
	s_add_u32 s38, s38, 0x80080
	s_addc_u32 s39, s39, 0
	s_add_u32 s59, s40, 0x100
	v_mov_b32_e32 v2, 0
	s_addc_u32 s60, s41, 0
	s_mov_b32 s61, -2
	v_mov_b32_e32 v3, v2
	v_mov_b32_e32 v4, v2
	v_mov_b32_e32 v5, v2
	v_mov_b32_e32 v6, v2
	v_mov_b32_e32 v7, v2
	v_mov_b32_e32 v8, v2
	v_mov_b32_e32 v9, v2
	s_waitcnt vmcnt(0)
	v_mov_b32_e32 v18, v2
	v_mov_b32_e32 v19, v2
	v_mov_b32_e32 v20, v2
	v_mov_b32_e32 v21, v2
	v_mov_b32_e32 v22, v2
	v_mov_b32_e32 v23, v2
	v_mov_b32_e32 v24, v2
	v_mov_b32_e32 v25, v2
	v_mov_b32_e32 v34, v2
	v_mov_b32_e32 v35, v2
	v_mov_b32_e32 v36, v2
	v_mov_b32_e32 v37, v2
	v_mov_b32_e32 v38, v2
	v_mov_b32_e32 v39, v2
	v_mov_b32_e32 v40, v2
	v_mov_b32_e32 v41, v2
	v_mov_b32_e32 v50, v2
	v_mov_b32_e32 v51, v2
	v_mov_b32_e32 v52, v2
	v_mov_b32_e32 v53, v2
	v_mov_b32_e32 v54, v2
	v_mov_b32_e32 v55, v2
	v_mov_b32_e32 v56, v2
	v_mov_b32_e32 v57, v2
	v_mov_b32_e32 v10, v2
	v_mov_b32_e32 v11, v2
	v_mov_b32_e32 v12, v2
	v_mov_b32_e32 v13, v2
	v_mov_b32_e32 v14, v2
	v_mov_b32_e32 v15, v2
	v_mov_b32_e32 v16, v2
	v_mov_b32_e32 v17, v2
	v_mov_b32_e32 v26, v2
	v_mov_b32_e32 v27, v2
	v_mov_b32_e32 v28, v2
	v_mov_b32_e32 v29, v2
	v_mov_b32_e32 v30, v2
	v_mov_b32_e32 v31, v2
	v_mov_b32_e32 v32, v2
	v_mov_b32_e32 v33, v2
	v_mov_b32_e32 v42, v2
	v_mov_b32_e32 v43, v2
	v_mov_b32_e32 v44, v2
	v_mov_b32_e32 v45, v2
	v_mov_b32_e32 v46, v2
	v_mov_b32_e32 v47, v2
	v_mov_b32_e32 v48, v2
	v_mov_b32_e32 v49, v2
	v_mov_b32_e32 v58, v2
	v_mov_b32_e32 v59, v2
	v_mov_b32_e32 v60, v2
	v_mov_b32_e32 v61, v2
	v_mov_b32_e32 v62, v2
	v_mov_b32_e32 v63, v2
	v_mov_b32_e32 v64, v2
	v_mov_b32_e32 v65, v2
	v_mov_b32_e32 v66, v2
	v_mov_b32_e32 v67, v2
	v_mov_b32_e32 v68, v2
	v_mov_b32_e32 v69, v2
	v_mov_b32_e32 v70, v2
	v_mov_b32_e32 v71, v2
	v_mov_b32_e32 v72, v2
	v_mov_b32_e32 v73, v2
	v_mov_b32_e32 v82, v2
	v_mov_b32_e32 v83, v2
	v_mov_b32_e32 v84, v2
	v_mov_b32_e32 v85, v2
	v_mov_b32_e32 v86, v2
	v_mov_b32_e32 v87, v2
	v_mov_b32_e32 v88, v2
	v_mov_b32_e32 v89, v2
	v_mov_b32_e32 v98, v2
	v_mov_b32_e32 v99, v2
	v_mov_b32_e32 v100, v2
	v_mov_b32_e32 v101, v2
	v_mov_b32_e32 v102, v2
	v_mov_b32_e32 v103, v2
	v_mov_b32_e32 v104, v2
	v_mov_b32_e32 v105, v2
	v_mov_b32_e32 v130, v2
	v_mov_b32_e32 v131, v2
	v_mov_b32_e32 v132, v2
	v_mov_b32_e32 v133, v2
	v_mov_b32_e32 v134, v2
	v_mov_b32_e32 v135, v2
	v_mov_b32_e32 v136, v2
	v_mov_b32_e32 v137, v2
	v_mov_b32_e32 v74, v2
	v_mov_b32_e32 v75, v2
	v_mov_b32_e32 v76, v2
	v_mov_b32_e32 v77, v2
	v_mov_b32_e32 v78, v2
	v_mov_b32_e32 v79, v2
	v_mov_b32_e32 v80, v2
	v_mov_b32_e32 v81, v2
	v_mov_b32_e32 v90, v2
	v_mov_b32_e32 v91, v2
	v_mov_b32_e32 v92, v2
	v_mov_b32_e32 v93, v2
	v_mov_b32_e32 v94, v2
	v_mov_b32_e32 v95, v2
	v_mov_b32_e32 v96, v2
	v_mov_b32_e32 v97, v2
	v_mov_b32_e32 v114, v2
	v_mov_b32_e32 v115, v2
	v_mov_b32_e32 v116, v2
	v_mov_b32_e32 v117, v2
	v_mov_b32_e32 v118, v2
	v_mov_b32_e32 v119, v2
	v_mov_b32_e32 v120, v2
	v_mov_b32_e32 v121, v2
	v_mov_b32_e32 v138, v2
	v_mov_b32_e32 v139, v2
	v_mov_b32_e32 v140, v2
	v_mov_b32_e32 v141, v2
	v_mov_b32_e32 v142, v2
	v_mov_b32_e32 v143, v2
	v_mov_b32_e32 v144, v2
	v_mov_b32_e32 v145, v2
	v_lshl_or_b32 v228, s56, 8, v166
	v_ashrrev_i32_e32 v229, 31, v228
	v_lshl_add_u64 v[228:229], v[228:229], 2, s[20:21]
	global_load_dwordx4 v[232:235], v[228:229], off
	global_load_dwordx4 v[236:239], v[228:229], off offset:16
	global_load_dwordx4 v[240:243], v[228:229], off offset:528
	global_load_dwordx4 v[244:247], v[228:229], off offset:512
	v_lshl_add_u32 v228, s36, 8, v164
	v_ashrrev_i32_e32 v229, 31, v228
	v_lshl_add_u64 v[228:229], v[228:229], 2, s[8:9]
	global_load_dword v248, v[228:229], off
	global_load_dword v249, v[228:229], off offset:64
	global_load_dword v250, v[228:229], off offset:128
	global_load_dword v251, v[228:229], off offset:192
	global_load_dword v252, v[228:229], off offset:512
	global_load_dword v253, v[228:229], off offset:576
	global_load_dword v230, v[228:229], off offset:640
	global_load_dword v231, v[228:229], off offset:704

;     __device__ __forceinline__ void operator()(const i32x4 (&acc)[2][2][4][2], const Unit& u, int wr, int wc, int fr, int fq) const {
;         const int row0 = u.pm * BM + wr * 64 + fr, col0 = u.pn * BM + wc * 32 + 8 * fq;
;         f32x4 cs[2][2];
; #pragma unroll
;         for (int bj = 0; bj < 2; ++bj) { cs[bj][0] = *(const f32x4*)(cscale + col0 + bj * HALF); cs[bj][1] = *(const f32x4*)(cscale + col0 + bj * HALF + 4); }
;         float rsv[2][4];
; #pragma unroll
;         for (int ai = 0; ai < 2; ++ai)
; #pragma unroll
;             for (int m = 0; m < 4; ++m) rsv[ai][m] = rowq[row0 + ai * HALF + m * 16];
; #pragma unroll
;         for (int ai = 0; ai < 2; ++ai)
; #pragma unroll
;             for (int m = 0; m < 4; ++m) { const int row = row0 + ai * HALF + m * 16; const float rs = rsv[ai][m]; bf16_t* rowp = O + (size_t)row * ldc + col0;
; #pragma unroll
;                 for (int bj = 0; bj < 2; ++bj) { const i32x4 a0 = acc[ai][bj][m][0], a1 = acc[ai][bj][m][1];
;                     f32x4 v0 = (f32x4){(float)a0[0], (float)a0[1], (float)a0[2], (float)a0[3]} * cs[bj][0] * rs, v1 = (f32x4){(float)a1[0], (float)a1[1], (float)a1[2], (float)a1[3]} * cs[bj][1] * rs;
; #pragma unroll
;                     for (int j = 0; j < 4; ++j) { const float a = fmaxf(v0[j], 0.f), b = fmaxf(v1[j], 0.f); v0[j] = a * a; v1[j] = b * b; }
.LBB0_1481:
	v_lshl_or_b32 v170, s56, 8, v166
	v_lshl_add_u32 v172, s36, 8, v164
	v_ashrrev_i32_e32 v171, 31, v170
	v_ashrrev_i32_e32 v173, 31, v172
	v_lshl_add_u64 v[110:111], v[170:171], 2, s[20:21]
	v_lshl_add_u64 v[174:175], v[172:173], 2, s[8:9]
	s_nop 0
	v_or_b32_e32 v196, 16, v172
	v_ashrrev_i32_e32 v197, 31, v196
	v_cvt_f32_i32_e32 v187, v141
	v_cvt_f32_i32_e32 v186, v140
	v_lshl_add_u64 v[140:141], v[196:197], 2, s[8:9]
	v_cvt_f32_i32_e32 v178, v142
	v_or_b32_e32 v198, 32, v172
	v_or_b32_e32 v142, 48, v172
	v_mov_b64_e32 v[162:163], s[90:91]
	v_cvt_f32_i32_e32 v179, v143
	v_ashrrev_i32_e32 v199, 31, v198
	v_ashrrev_i32_e32 v143, 31, v142
	v_cvt_f32_i32_e32 v181, v145
	v_cvt_f32_i32_e32 v180, v144
	v_cvt_f32_i32_e32 v185, v139
	v_cvt_f32_i32_e32 v184, v138
	v_cvt_f32_i32_e32 v195, v133
	v_cvt_f32_i32_e32 v194, v132
	v_mad_i64_i32 v[138:139], s[38:39], v172, s55, v[162:163]
	v_lshlrev_b64 v[132:133], 1, v[170:171]
	v_lshl_add_u64 v[144:145], v[198:199], 2, s[8:9]
	v_lshl_add_u64 v[140:141], v[142:143], 2, s[8:9]
	v_cvt_f32_i32_e32 v188, v134
	v_cvt_f32_i32_e32 v190, v136
	v_cvt_f32_i32_e32 v192, v130
	v_lshl_add_u64 v[202:203], v[138:139], 0, v[132:133]
	s_nop 0
	s_nop 0
	s_nop 0
	v_cvt_f32_i32_e32 v189, v135
	v_cvt_f32_i32_e32 v191, v137
	v_cvt_f32_i32_e32 v115, v115
	v_cvt_f32_i32_e32 v114, v114
	v_cvt_f32_i32_e32 v193, v131
	v_add_u32_e32 v183, 0x80, v172
	v_add_u32_e32 v137, 0x90, v172
	v_add_u32_e32 v135, 0xa0, v172
	v_add_u32_e32 v131, 0xb0, v172
	v_cvt_f32_i32_e32 v119, v119
	v_cvt_f32_i32_e32 v118, v118
	v_cvt_f32_i32_e32 v117, v117
	v_cvt_f32_i32_e32 v116, v116
	v_cvt_f32_i32_e32 v121, v121
	v_cvt_f32_i32_e32 v120, v120
	v_cvt_f32_i32_e32 v99, v99
	v_cvt_f32_i32_e32 v101, v101
	v_cvt_f32_i32_e32 v100, v100
	v_cvt_f32_i32_e32 v98, v98
	v_cvt_f32_i32_e32 v103, v103
	v_cvt_f32_i32_e32 v105, v105
	v_cvt_f32_i32_e32 v104, v104
	v_cvt_f32_i32_e32 v102, v102
	v_cvt_f32_i32_e32 v91, v91
	v_cvt_f32_i32_e32 v90, v90
	v_cvt_f32_i32_e32 v95, v95
	v_cvt_f32_i32_e32 v94, v94
	v_cvt_f32_i32_e32 v93, v93
	v_cvt_f32_i32_e32 v92, v92
	v_cvt_f32_i32_e32 v97, v97
	v_cvt_f32_i32_e32 v96, v96
	v_cvt_f32_i32_e32 v83, v83
	v_cvt_f32_i32_e32 v85, v85
	v_cvt_f32_i32_e32 v84, v84
	v_cvt_f32_i32_e32 v82, v82
	v_cvt_f32_i32_e32 v87, v87
	v_cvt_f32_i32_e32 v89, v89
	v_cvt_f32_i32_e32 v88, v88
	v_cvt_f32_i32_e32 v86, v86
	v_cvt_f32_i32_e32 v75, v75
	v_cvt_f32_i32_e32 v74, v74
	v_cvt_f32_i32_e32 v79, v79
	v_cvt_f32_i32_e32 v78, v78
	v_cvt_f32_i32_e32 v77, v77
	v_cvt_f32_i32_e32 v76, v76
	v_cvt_f32_i32_e32 v81, v81
	s_waitcnt vmcnt(0)
	v_mov_b32_e32 v126, v232
	v_mov_b32_e32 v127, v233
	v_mov_b32_e32 v128, v234
	v_mov_b32_e32 v129, v235
	v_mov_b32_e32 v122, v236
	v_mov_b32_e32 v123, v237
	v_mov_b32_e32 v124, v238
	v_mov_b32_e32 v125, v239
	v_mov_b32_e32 v106, v240
	v_mov_b32_e32 v107, v241
	v_mov_b32_e32 v108, v242
	v_mov_b32_e32 v109, v243
	v_mov_b32_e32 v110, v244
	v_mov_b32_e32 v111, v245
	v_mov_b32_e32 v112, v246
	v_mov_b32_e32 v113, v247
	v_mov_b32_e32 v176, v248
	v_mov_b32_e32 v200, v249
	v_mov_b32_e32 v144, v250
	v_mov_b32_e32 v140, v251
	v_mov_b32_e32 v138, v252
	v_mov_b32_e32 v136, v253
	v_mov_b32_e32 v134, v230
	v_mov_b32_e32 v130, v231
	v_pk_mul_f32 v[170:171], v[128:129], v[180:181]
	v_pk_mul_f32 v[172:173], v[126:127], v[178:179]
	v_pk_mul_f32 v[174:175], v[124:125], v[186:187]
	v_pk_mul_f32 v[178:179], v[122:123], v[184:185]
	v_pk_mul_f32 v[180:181], v[112:113], v[190:191]
	v_pk_mul_f32 v[170:171], v[170:171], v[176:177] op_sel_hi:[1,0]
	v_pk_mul_f32 v[172:173], v[172:173], v[176:177] op_sel_hi:[1,0]
	v_pk_mul_f32 v[174:175], v[174:175], v[176:177] op_sel_hi:[1,0]
	v_max_f32_e32 v171, 0, v171
	v_pk_mul_f32 v[184:185], v[110:111], v[188:189]
	v_pk_mul_f32 v[186:187], v[108:109], v[194:195]
	v_pk_mul_f32 v[178:179], v[178:179], v[176:177] op_sel_hi:[1,0]
	v_max_f32_e32 v139, 0, v172
	v_max_f32_e32 v143, 0, v173
	v_max_f32_e32 v170, 0, v170
	v_max_f32_e32 v173, 0, v175
	v_mul_f32_e32 v171, v171, v171
	v_pk_mul_f32 v[180:181], v[180:181], v[176:177] op_sel_hi:[1,0]
	v_pk_mul_f32 v[184:185], v[184:185], v[176:177] op_sel_hi:[1,0]
	v_pk_mul_f32 v[186:187], v[186:187], v[176:177] op_sel_hi:[1,0]
	v_max_f32_e32 v141, 0, v178
	v_max_f32_e32 v145, 0, v179
	v_max_f32_e32 v172, 0, v174
	v_mul_f32_e32 v139, v139, v139
	v_mul_f32_e32 v143, v143, v143
	v_mul_f32_e32 v174, v170, v170
	v_mul_f32_e32 v173, v173, v173
	v_cvt_pk_bf16_f32 v170, v139, v143
	v_cvt_pk_bf16_f32 v171, v174, v171
	v_pk_mul_f32 v[114:115], v[122:123], v[114:115]
	v_pk_mul_f32 v[188:189], v[106:107], v[192:193]
	v_mul_f32_e32 v141, v141, v141
	v_mul_f32_e32 v145, v145, v145
	v_mul_f32_e32 v175, v172, v172
	v_cvt_pk_bf16_f32 v172, v141, v145
	v_cvt_pk_bf16_f32 v173, v175, v173
	global_store_dwordx4 v[202:203], v[170:173], off
	v_max_f32_e32 v139, 0, v184
	v_pk_mul_f32 v[118:119], v[126:127], v[118:119]
	v_max_f32_e32 v170, 0, v180
	v_max_f32_e32 v171, 0, v186
	v_pk_mul_f32 v[116:117], v[124:125], v[116:117]
	v_pk_mul_f32 v[114:115], v[114:115], v[200:201] op_sel_hi:[1,0]
	v_pk_mul_f32 v[176:177], v[188:189], v[176:177] op_sel_hi:[1,0]
	v_mul_f32_e32 v139, v139, v139
	v_max_f32_e32 v143, 0, v185
	v_mul_f32_e32 v172, v170, v170
	v_mul_f32_e32 v173, v171, v171
	v_max_f32_e32 v170, 0, v181
	v_max_f32_e32 v171, 0, v187
	v_pk_mul_f32 v[120:121], v[128:129], v[120:121]
	v_pk_mul_f32 v[118:119], v[118:119], v[200:201] op_sel_hi:[1,0]
	v_pk_mul_f32 v[116:117], v[116:117], v[200:201] op_sel_hi:[1,0]
	v_max_f32_e32 v114, 0, v114
	v_max_f32_e32 v141, 0, v176
	v_max_f32_e32 v145, 0, v177
	v_mul_f32_e32 v143, v143, v143
	v_mul_f32_e32 v174, v170, v170
	v_mul_f32_e32 v175, v171, v171
; __device__ __forceinline__ unsigned cvt_pk_bf16(float lo, float hi) { unsigned r; asm volatile("v_cvt_pk_bf16_f32 %0, %1, %2" : "=v"(r) : "v"(lo), "v"(hi)); return r; }
;     __device__ __forceinline__ void operator()(const i32x4 (&acc)[2][2][4][2], const Unit& u, int wr, int wc, int fr, int fq) const {
;     ...
;         for (int ai = 0; ai < 2; ++ai)
; #pragma unroll
;             for (int m = 0; m < 4; ++m) { const int row = row0 + ai * HALF + m * 16; const float rs = rsv[ai][m]; bf16_t* rowp = O + (size_t)row * ldc + col0;
; #pragma unroll
;                 for (int bj = 0; bj < 2; ++bj) { const i32x4 a0 = acc[ai][bj][m][0], a1 = acc[ai][bj][m][1];
;                     f32x4 v0 = (f32x4){(float)a0[0], (float)a0[1], (float)a0[2], (float)a0[3]} * cs[bj][0] * rs, v1 = (f32x4){(float)a1[0], (float)a1[1], (float)a1[2], (float)a1[3]} * cs[bj][1] * rs;
; #pragma unroll
;                     for (int j = 0; j < 4; ++j) { const float a = fmaxf(v0[j], 0.f), b = fmaxf(v1[j], 0.f); v0[j] = a * a; v1[j] = b * b; }
;                     u32x4 w; w.x = cvt_pk_bf16(v0[0], v0[1]); w.y = cvt_pk_bf16(v0[2], v0[3]); w.z = cvt_pk_bf16(v1[0], v1[1]); w.w = cvt_pk_bf16(v1[2], v1[3]);
;                     *(u32x4*)(rowp + bj * HALF) = w; } }
	v_cvt_pk_bf16_f32 v170, v139, v143
	v_cvt_pk_bf16_f32 v171, v172, v174
	v_pk_mul_f32 v[120:121], v[120:121], v[200:201] op_sel_hi:[1,0]
	v_mul_f32_e32 v139, v114, v114
	v_max_f32_e32 v114, 0, v119
	v_max_f32_e32 v115, 0, v115
	v_max_f32_e32 v116, 0, v116
	v_pk_mul_f32 v[100:101], v[108:109], v[100:101]
	v_pk_mul_f32 v[98:99], v[106:107], v[98:99]
	v_mul_f32_e32 v141, v141, v141
	v_mul_f32_e32 v145, v145, v145
	v_cvt_pk_bf16_f32 v172, v141, v145
	v_cvt_pk_bf16_f32 v173, v173, v175
	global_store_dwordx4 v[202:203], v[170:173], off offset:256
	v_max_f32_e32 v118, 0, v118
	v_mul_f32_e32 v114, v114, v114
	v_mad_i64_i32 v[170:171], s[38:39], v196, s55, v[162:163]
	v_mul_f32_e32 v119, v115, v115
	v_max_f32_e32 v115, 0, v120
	v_mul_f32_e32 v120, v116, v116
	v_max_f32_e32 v116, 0, v121
	v_max_f32_e32 v117, 0, v117
	v_pk_mul_f32 v[104:105], v[112:113], v[104:105]
	v_pk_mul_f32 v[102:103], v[110:111], v[102:103]
	v_pk_mul_f32 v[100:101], v[100:101], v[200:201] op_sel_hi:[1,0]
	v_pk_mul_f32 v[98:99], v[98:99], v[200:201] op_sel_hi:[1,0]
	v_lshl_add_u64 v[170:171], v[170:171], 0, v[132:133]
	v_mul_f32_e32 v118, v118, v118
	v_mul_f32_e32 v115, v115, v115
	v_mul_f32_e32 v116, v116, v116
	v_mul_f32_e32 v117, v117, v117
	v_cvt_pk_bf16_f32 v114, v118, v114
	v_pk_mul_f32 v[104:105], v[104:105], v[200:201] op_sel_hi:[1,0]
	v_pk_mul_f32 v[102:103], v[102:103], v[200:201] op_sel_hi:[1,0]
	v_max_f32_e32 v98, 0, v98
	v_max_f32_e32 v99, 0, v99
	v_max_f32_e32 v100, 0, v100
	v_cvt_pk_bf16_f32 v115, v115, v116
	v_cvt_pk_bf16_f32 v116, v139, v119
	v_cvt_pk_bf16_f32 v117, v120, v117
	global_store_dwordx4 v[170:171], v[114:117], off
	v_pk_mul_f32 v[90:91], v[122:123], v[90:91]
	v_max_f32_e32 v102, 0, v102
	v_mul_f32_e32 v114, v98, v98
	v_max_f32_e32 v98, 0, v103
	v_mul_f32_e32 v103, v99, v99
	v_max_f32_e32 v99, 0, v104
	v_mul_f32_e32 v104, v100, v100
	v_max_f32_e32 v100, 0, v105
	v_mul_f32_e32 v98, v98, v98
	v_mul_f32_e32 v99, v99, v99
	v_max_f32_e32 v101, 0, v101
	v_mul_f32_e32 v100, v100, v100
	v_pk_mul_f32 v[94:95], v[126:127], v[94:95]
	v_pk_mul_f32 v[92:93], v[124:125], v[92:93]
	v_pk_mul_f32 v[90:91], v[90:91], v[144:145] op_sel_hi:[1,0]
	v_mul_f32_e32 v102, v102, v102
	v_mul_f32_e32 v101, v101, v101
	v_cvt_pk_bf16_f32 v98, v102, v98
	v_cvt_pk_bf16_f32 v99, v99, v100
	v_cvt_pk_bf16_f32 v100, v114, v103
	v_pk_mul_f32 v[96:97], v[128:129], v[96:97]
	v_pk_mul_f32 v[94:95], v[94:95], v[144:145] op_sel_hi:[1,0]
	v_pk_mul_f32 v[92:93], v[92:93], v[144:145] op_sel_hi:[1,0]
	v_max_f32_e32 v90, 0, v90
	v_cvt_pk_bf16_f32 v101, v104, v101
	global_store_dwordx4 v[170:171], v[98:101], off offset:256
	v_pk_mul_f32 v[96:97], v[96:97], v[144:145] op_sel_hi:[1,0]
	v_max_f32_e32 v91, 0, v91
	v_mul_f32_e32 v100, v90, v90
	v_max_f32_e32 v90, 0, v95
	v_max_f32_e32 v92, 0, v92
	v_pk_mul_f32 v[84:85], v[108:109], v[84:85]
	v_pk_mul_f32 v[82:83], v[106:107], v[82:83]
	v_mad_i64_i32 v[98:99], s[38:39], v198, s55, v[162:163]
	v_max_f32_e32 v94, 0, v94
	v_mul_f32_e32 v90, v90, v90
	v_mul_f32_e32 v95, v91, v91
	v_max_f32_e32 v91, 0, v96
	v_mul_f32_e32 v96, v92, v92
	v_max_f32_e32 v92, 0, v97
	v_max_f32_e32 v93, 0, v93
	v_pk_mul_f32 v[88:89], v[112:113], v[88:89]
	v_pk_mul_f32 v[86:87], v[110:111], v[86:87]
	v_pk_mul_f32 v[84:85], v[84:85], v[144:145] op_sel_hi:[1,0]
	v_pk_mul_f32 v[82:83], v[82:83], v[144:145] op_sel_hi:[1,0]
	v_cvt_f32_i32_e32 v80, v80
	v_lshl_add_u64 v[98:99], v[98:99], 0, v[132:133]
	v_mul_f32_e32 v94, v94, v94
	v_mul_f32_e32 v91, v91, v91
	v_mul_f32_e32 v92, v92, v92
	v_mul_f32_e32 v93, v93, v93
	v_cvt_pk_bf16_f32 v90, v94, v90
	v_pk_mul_f32 v[88:89], v[88:89], v[144:145] op_sel_hi:[1,0]
	v_pk_mul_f32 v[86:87], v[86:87], v[144:145] op_sel_hi:[1,0]
	v_max_f32_e32 v82, 0, v82
	v_max_f32_e32 v83, 0, v83
	v_max_f32_e32 v84, 0, v84
	v_cvt_f32_i32_e32 v67, v67
	v_cvt_f32_i32_e32 v69, v69
	v_cvt_f32_i32_e32 v68, v68
	v_cvt_f32_i32_e32 v66, v66
	v_cvt_pk_bf16_f32 v91, v91, v92
	v_cvt_pk_bf16_f32 v92, v100, v95
	v_cvt_pk_bf16_f32 v93, v96, v93
	global_store_dwordx4 v[98:99], v[90:93], off
	v_pk_mul_f32 v[74:75], v[122:123], v[74:75]
	v_cvt_f32_i32_e32 v71, v71
	v_mul_f32_e32 v90, v82, v82
	v_max_f32_e32 v82, 0, v87
	v_mul_f32_e32 v87, v83, v83
	v_max_f32_e32 v83, 0, v88
	v_mul_f32_e32 v88, v84, v84
	v_max_f32_e32 v84, 0, v89
	v_cvt_f32_i32_e32 v73, v73
	v_cvt_f32_i32_e32 v72, v72
	v_cvt_f32_i32_e32 v70, v70
	v_max_f32_e32 v86, 0, v86
	v_mul_f32_e32 v82, v82, v82
	v_mul_f32_e32 v83, v83, v83
	v_max_f32_e32 v85, 0, v85
	v_mul_f32_e32 v84, v84, v84
	v_pk_mul_f32 v[78:79], v[126:127], v[78:79]
	v_pk_mul_f32 v[76:77], v[124:125], v[76:77]
	v_pk_mul_f32 v[74:75], v[74:75], v[140:141] op_sel_hi:[1,0]
	v_mul_f32_e32 v86, v86, v86
	v_mul_f32_e32 v85, v85, v85
	v_cvt_pk_bf16_f32 v82, v86, v82
	v_cvt_pk_bf16_f32 v83, v83, v84
	v_cvt_pk_bf16_f32 v84, v90, v87
	v_pk_mul_f32 v[80:81], v[128:129], v[80:81]
	v_pk_mul_f32 v[78:79], v[78:79], v[140:141] op_sel_hi:[1,0]
	v_pk_mul_f32 v[76:77], v[76:77], v[140:141] op_sel_hi:[1,0]
	v_max_f32_e32 v74, 0, v74
	v_cvt_f32_i32_e32 v59, v59
	v_cvt_f32_i32_e32 v58, v58
	v_cvt_pk_bf16_f32 v85, v88, v85
	global_store_dwordx4 v[98:99], v[82:85], off offset:256
	v_pk_mul_f32 v[80:81], v[80:81], v[140:141] op_sel_hi:[1,0]
	v_max_f32_e32 v75, 0, v75
	v_mul_f32_e32 v84, v74, v74
	v_max_f32_e32 v74, 0, v79
	v_max_f32_e32 v76, 0, v76
	v_pk_mul_f32 v[68:69], v[108:109], v[68:69]
	v_pk_mul_f32 v[66:67], v[106:107], v[66:67]
	v_cvt_f32_i32_e32 v63, v63
	v_cvt_f32_i32_e32 v62, v62
	v_cvt_f32_i32_e32 v61, v61
	v_cvt_f32_i32_e32 v60, v60
	v_mad_i64_i32 v[82:83], s[38:39], v142, s55, v[162:163]
	v_max_f32_e32 v78, 0, v78
	v_mul_f32_e32 v74, v74, v74
	v_mul_f32_e32 v79, v75, v75
; __device__ __forceinline__ unsigned cvt_pk_bf16(float lo, float hi) { unsigned r; asm volatile("v_cvt_pk_bf16_f32 %0, %1, %2" : "=v"(r) : "v"(lo), "v"(hi)); return r; }
;     __device__ __forceinline__ void operator()(const i32x4 (&acc)[2][2][4][2], const Unit& u, int wr, int wc, int fr, int fq) const {
;     ...
;         for (int ai = 0; ai < 2; ++ai)
; #pragma unroll
;             for (int m = 0; m < 4; ++m) { const int row = row0 + ai * HALF + m * 16; const float rs = rsv[ai][m]; bf16_t* rowp = O + (size_t)row * ldc + col0;
; #pragma unroll
;                 for (int bj = 0; bj < 2; ++bj) { const i32x4 a0 = acc[ai][bj][m][0], a1 = acc[ai][bj][m][1];
;                     f32x4 v0 = (f32x4){(float)a0[0], (float)a0[1], (float)a0[2], (float)a0[3]} * cs[bj][0] * rs, v1 = (f32x4){(float)a1[0], (float)a1[1], (float)a1[2], (float)a1[3]} * cs[bj][1] * rs;
; #pragma unroll
;                     for (int j = 0; j < 4; ++j) { const float a = fmaxf(v0[j], 0.f), b = fmaxf(v1[j], 0.f); v0[j] = a * a; v1[j] = b * b; }
;                     u32x4 w; w.x = cvt_pk_bf16(v0[0], v0[1]); w.y = cvt_pk_bf16(v0[2], v0[3]); w.z = cvt_pk_bf16(v1[0], v1[1]); w.w = cvt_pk_bf16(v1[2], v1[3]);
;                     *(u32x4*)(rowp + bj * HALF) = w; } }
	v_max_f32_e32 v75, 0, v80
	v_mul_f32_e32 v80, v76, v76
	v_max_f32_e32 v76, 0, v81
	v_max_f32_e32 v77, 0, v77
	v_pk_mul_f32 v[72:73], v[112:113], v[72:73]
	v_pk_mul_f32 v[70:71], v[110:111], v[70:71]
	v_pk_mul_f32 v[68:69], v[68:69], v[140:141] op_sel_hi:[1,0]
	v_pk_mul_f32 v[66:67], v[66:67], v[140:141] op_sel_hi:[1,0]
	v_cvt_f32_i32_e32 v65, v65
	v_cvt_f32_i32_e32 v64, v64
	v_lshl_add_u64 v[82:83], v[82:83], 0, v[132:133]
	v_mul_f32_e32 v78, v78, v78
	v_mul_f32_e32 v75, v75, v75
	v_mul_f32_e32 v76, v76, v76
	v_mul_f32_e32 v77, v77, v77
	v_cvt_pk_bf16_f32 v74, v78, v74
	v_pk_mul_f32 v[72:73], v[72:73], v[140:141] op_sel_hi:[1,0]
	v_pk_mul_f32 v[70:71], v[70:71], v[140:141] op_sel_hi:[1,0]
	v_max_f32_e32 v66, 0, v66
	v_max_f32_e32 v67, 0, v67
	v_max_f32_e32 v68, 0, v68
	v_cvt_f32_i32_e32 v51, v51
	v_cvt_f32_i32_e32 v53, v53
	v_cvt_f32_i32_e32 v52, v52
	v_cvt_f32_i32_e32 v50, v50
	v_cvt_pk_bf16_f32 v75, v75, v76
	v_cvt_pk_bf16_f32 v76, v84, v79
	v_cvt_pk_bf16_f32 v77, v80, v77
	global_store_dwordx4 v[82:83], v[74:77], off
	v_pk_mul_f32 v[58:59], v[122:123], v[58:59]
	v_cvt_f32_i32_e32 v55, v55
	v_mul_f32_e32 v74, v66, v66
	v_max_f32_e32 v66, 0, v71
	v_mul_f32_e32 v71, v67, v67
	v_max_f32_e32 v67, 0, v72
	v_mul_f32_e32 v72, v68, v68
	v_max_f32_e32 v68, 0, v73
	v_cvt_f32_i32_e32 v57, v57
	v_cvt_f32_i32_e32 v56, v56
	v_cvt_f32_i32_e32 v54, v54
	v_max_f32_e32 v70, 0, v70
	v_mul_f32_e32 v66, v66, v66
	v_mul_f32_e32 v67, v67, v67
	v_max_f32_e32 v69, 0, v69
	v_mul_f32_e32 v68, v68, v68
	v_pk_mul_f32 v[62:63], v[126:127], v[62:63]
	v_pk_mul_f32 v[60:61], v[124:125], v[60:61]
	v_pk_mul_f32 v[58:59], v[58:59], v[138:139] op_sel_hi:[1,0]
	v_mul_f32_e32 v70, v70, v70
	v_mul_f32_e32 v69, v69, v69
	v_cvt_pk_bf16_f32 v66, v70, v66
	v_cvt_pk_bf16_f32 v67, v67, v68
	v_cvt_pk_bf16_f32 v68, v74, v71
	v_pk_mul_f32 v[64:65], v[128:129], v[64:65]
	v_pk_mul_f32 v[62:63], v[62:63], v[138:139] op_sel_hi:[1,0]
	v_pk_mul_f32 v[60:61], v[60:61], v[138:139] op_sel_hi:[1,0]
	v_max_f32_e32 v58, 0, v58
	v_cvt_f32_i32_e32 v43, v43
	v_cvt_f32_i32_e32 v42, v42
	v_cvt_pk_bf16_f32 v69, v72, v69
	global_store_dwordx4 v[82:83], v[66:69], off offset:256
	v_pk_mul_f32 v[64:65], v[64:65], v[138:139] op_sel_hi:[1,0]
	v_max_f32_e32 v59, 0, v59
	v_mul_f32_e32 v68, v58, v58
	v_max_f32_e32 v58, 0, v63
	v_max_f32_e32 v60, 0, v60
	v_pk_mul_f32 v[52:53], v[108:109], v[52:53]
	v_pk_mul_f32 v[50:51], v[106:107], v[50:51]
	v_cvt_f32_i32_e32 v47, v47
	v_cvt_f32_i32_e32 v46, v46
	v_cvt_f32_i32_e32 v45, v45
	v_cvt_f32_i32_e32 v44, v44
	v_mad_i64_i32 v[66:67], s[38:39], v183, s55, v[162:163]
	v_max_f32_e32 v62, 0, v62
	v_mul_f32_e32 v58, v58, v58
	v_mul_f32_e32 v63, v59, v59
	v_max_f32_e32 v59, 0, v64
	v_mul_f32_e32 v64, v60, v60
	v_max_f32_e32 v60, 0, v65
	v_max_f32_e32 v61, 0, v61
	v_pk_mul_f32 v[56:57], v[112:113], v[56:57]
	v_pk_mul_f32 v[54:55], v[110:111], v[54:55]
	v_pk_mul_f32 v[52:53], v[52:53], v[138:139] op_sel_hi:[1,0]
	v_pk_mul_f32 v[50:51], v[50:51], v[138:139] op_sel_hi:[1,0]
	v_cvt_f32_i32_e32 v49, v49
	v_cvt_f32_i32_e32 v48, v48
	v_lshl_add_u64 v[66:67], v[66:67], 0, v[132:133]
	v_mul_f32_e32 v62, v62, v62
	v_mul_f32_e32 v59, v59, v59
	v_mul_f32_e32 v60, v60, v60
	v_mul_f32_e32 v61, v61, v61
	v_cvt_pk_bf16_f32 v58, v62, v58
	v_pk_mul_f32 v[56:57], v[56:57], v[138:139] op_sel_hi:[1,0]
	v_pk_mul_f32 v[54:55], v[54:55], v[138:139] op_sel_hi:[1,0]
	v_max_f32_e32 v50, 0, v50
	v_max_f32_e32 v51, 0, v51
	v_max_f32_e32 v52, 0, v52
	v_cvt_f32_i32_e32 v35, v35
	v_cvt_f32_i32_e32 v37, v37
	v_cvt_f32_i32_e32 v36, v36
	v_cvt_f32_i32_e32 v34, v34
	v_cvt_pk_bf16_f32 v59, v59, v60
	v_cvt_pk_bf16_f32 v60, v68, v63
	v_cvt_pk_bf16_f32 v61, v64, v61
	global_store_dwordx4 v[66:67], v[58:61], off
	v_pk_mul_f32 v[42:43], v[122:123], v[42:43]
	v_cvt_f32_i32_e32 v39, v39
	v_mul_f32_e32 v58, v50, v50
	v_max_f32_e32 v50, 0, v55
	v_mul_f32_e32 v55, v51, v51
	v_max_f32_e32 v51, 0, v56
	v_mul_f32_e32 v56, v52, v52
	v_max_f32_e32 v52, 0, v57
	v_cvt_f32_i32_e32 v41, v41
	v_cvt_f32_i32_e32 v40, v40
	v_cvt_f32_i32_e32 v38, v38
	v_max_f32_e32 v54, 0, v54
	v_mul_f32_e32 v50, v50, v50
	v_mul_f32_e32 v51, v51, v51
	v_max_f32_e32 v53, 0, v53
	v_mul_f32_e32 v52, v52, v52
	v_pk_mul_f32 v[46:47], v[126:127], v[46:47]
	v_pk_mul_f32 v[44:45], v[124:125], v[44:45]
	v_pk_mul_f32 v[42:43], v[42:43], v[136:137] op_sel_hi:[1,0]
	v_mul_f32_e32 v54, v54, v54
	v_mul_f32_e32 v53, v53, v53
	v_cvt_pk_bf16_f32 v50, v54, v50
	v_cvt_pk_bf16_f32 v51, v51, v52
	v_cvt_pk_bf16_f32 v52, v58, v55
	v_pk_mul_f32 v[48:49], v[128:129], v[48:49]
	v_pk_mul_f32 v[46:47], v[46:47], v[136:137] op_sel_hi:[1,0]
	v_pk_mul_f32 v[44:45], v[44:45], v[136:137] op_sel_hi:[1,0]
	v_max_f32_e32 v42, 0, v42
	v_cvt_f32_i32_e32 v27, v27
	v_cvt_f32_i32_e32 v26, v26
	v_cvt_pk_bf16_f32 v53, v56, v53
	global_store_dwordx4 v[66:67], v[50:53], off offset:256
	v_pk_mul_f32 v[48:49], v[48:49], v[136:137] op_sel_hi:[1,0]
	v_max_f32_e32 v43, 0, v43
	v_mul_f32_e32 v52, v42, v42
	v_max_f32_e32 v42, 0, v47
	v_max_f32_e32 v44, 0, v44
	v_pk_mul_f32 v[36:37], v[108:109], v[36:37]
	v_pk_mul_f32 v[34:35], v[106:107], v[34:35]
	v_cvt_f32_i32_e32 v31, v31
	v_cvt_f32_i32_e32 v30, v30
	v_cvt_f32_i32_e32 v29, v29
	v_cvt_f32_i32_e32 v28, v28
	v_mad_i64_i32 v[50:51], s[38:39], v137, s55, v[162:163]
	v_max_f32_e32 v46, 0, v46
	v_mul_f32_e32 v42, v42, v42
	v_mul_f32_e32 v47, v43, v43
	v_max_f32_e32 v43, 0, v48
	v_mul_f32_e32 v48, v44, v44
	v_max_f32_e32 v44, 0, v49
	v_max_f32_e32 v45, 0, v45
	v_pk_mul_f32 v[40:41], v[112:113], v[40:41]
	v_pk_mul_f32 v[38:39], v[110:111], v[38:39]
	v_pk_mul_f32 v[36:37], v[36:37], v[136:137] op_sel_hi:[1,0]
	v_pk_mul_f32 v[34:35], v[34:35], v[136:137] op_sel_hi:[1,0]
; __device__ __forceinline__ unsigned cvt_pk_bf16(float lo, float hi) { unsigned r; asm volatile("v_cvt_pk_bf16_f32 %0, %1, %2" : "=v"(r) : "v"(lo), "v"(hi)); return r; }
;     __device__ __forceinline__ void operator()(const i32x4 (&acc)[2][2][4][2], const Unit& u, int wr, int wc, int fr, int fq) const {
;     ...
;         for (int ai = 0; ai < 2; ++ai)
; #pragma unroll
;             for (int m = 0; m < 4; ++m) { const int row = row0 + ai * HALF + m * 16; const float rs = rsv[ai][m]; bf16_t* rowp = O + (size_t)row * ldc + col0;
; #pragma unroll
;                 for (int bj = 0; bj < 2; ++bj) { const i32x4 a0 = acc[ai][bj][m][0], a1 = acc[ai][bj][m][1];
;                     f32x4 v0 = (f32x4){(float)a0[0], (float)a0[1], (float)a0[2], (float)a0[3]} * cs[bj][0] * rs, v1 = (f32x4){(float)a1[0], (float)a1[1], (float)a1[2], (float)a1[3]} * cs[bj][1] * rs;
; #pragma unroll
;                     for (int j = 0; j < 4; ++j) { const float a = fmaxf(v0[j], 0.f), b = fmaxf(v1[j], 0.f); v0[j] = a * a; v1[j] = b * b; }
;                     u32x4 w; w.x = cvt_pk_bf16(v0[0], v0[1]); w.y = cvt_pk_bf16(v0[2], v0[3]); w.z = cvt_pk_bf16(v1[0], v1[1]); w.w = cvt_pk_bf16(v1[2], v1[3]);
;                     *(u32x4*)(rowp + bj * HALF) = w; } }
	v_cvt_f32_i32_e32 v33, v33
	v_cvt_f32_i32_e32 v32, v32
	v_lshl_add_u64 v[50:51], v[50:51], 0, v[132:133]
	v_mul_f32_e32 v46, v46, v46
	v_mul_f32_e32 v43, v43, v43
	v_mul_f32_e32 v44, v44, v44
	v_mul_f32_e32 v45, v45, v45
	v_cvt_pk_bf16_f32 v42, v46, v42
	v_pk_mul_f32 v[40:41], v[40:41], v[136:137] op_sel_hi:[1,0]
	v_pk_mul_f32 v[38:39], v[38:39], v[136:137] op_sel_hi:[1,0]
	v_max_f32_e32 v34, 0, v34
	v_max_f32_e32 v35, 0, v35
	v_max_f32_e32 v36, 0, v36
	v_cvt_f32_i32_e32 v19, v19
	v_cvt_f32_i32_e32 v21, v21
	v_cvt_f32_i32_e32 v20, v20
	v_cvt_f32_i32_e32 v18, v18
	v_cvt_pk_bf16_f32 v43, v43, v44
	v_cvt_pk_bf16_f32 v44, v52, v47
	v_cvt_pk_bf16_f32 v45, v48, v45
	global_store_dwordx4 v[50:51], v[42:45], off
	v_pk_mul_f32 v[26:27], v[122:123], v[26:27]
	v_cvt_f32_i32_e32 v23, v23
	v_mul_f32_e32 v42, v34, v34
	v_max_f32_e32 v34, 0, v39
	v_mul_f32_e32 v39, v35, v35
	v_max_f32_e32 v35, 0, v40
	v_mul_f32_e32 v40, v36, v36
	v_max_f32_e32 v36, 0, v41
	v_cvt_f32_i32_e32 v25, v25
	v_cvt_f32_i32_e32 v24, v24
	v_cvt_f32_i32_e32 v22, v22
	v_max_f32_e32 v38, 0, v38
	v_mul_f32_e32 v34, v34, v34
	v_mul_f32_e32 v35, v35, v35
	v_max_f32_e32 v37, 0, v37
	v_mul_f32_e32 v36, v36, v36
	v_pk_mul_f32 v[30:31], v[126:127], v[30:31]
	v_pk_mul_f32 v[28:29], v[124:125], v[28:29]
	v_pk_mul_f32 v[26:27], v[26:27], v[134:135] op_sel_hi:[1,0]
	v_mul_f32_e32 v38, v38, v38
	v_mul_f32_e32 v37, v37, v37
	v_cvt_pk_bf16_f32 v34, v38, v34
	v_cvt_pk_bf16_f32 v35, v35, v36
	v_cvt_pk_bf16_f32 v36, v42, v39
	v_pk_mul_f32 v[32:33], v[128:129], v[32:33]
	v_pk_mul_f32 v[30:31], v[30:31], v[134:135] op_sel_hi:[1,0]
	v_pk_mul_f32 v[28:29], v[28:29], v[134:135] op_sel_hi:[1,0]
	v_max_f32_e32 v26, 0, v26
	v_cvt_f32_i32_e32 v11, v11
	v_cvt_f32_i32_e32 v10, v10
	v_cvt_pk_bf16_f32 v37, v40, v37
	global_store_dwordx4 v[50:51], v[34:37], off offset:256
	v_pk_mul_f32 v[32:33], v[32:33], v[134:135] op_sel_hi:[1,0]
	v_max_f32_e32 v27, 0, v27
	v_mul_f32_e32 v36, v26, v26
	v_max_f32_e32 v26, 0, v31
	v_max_f32_e32 v28, 0, v28
	v_pk_mul_f32 v[20:21], v[108:109], v[20:21]
	v_pk_mul_f32 v[18:19], v[106:107], v[18:19]
	v_cvt_f32_i32_e32 v15, v15
	v_cvt_f32_i32_e32 v14, v14
	v_cvt_f32_i32_e32 v13, v13
	v_cvt_f32_i32_e32 v12, v12
	v_mad_i64_i32 v[34:35], s[38:39], v135, s55, v[162:163]
	v_max_f32_e32 v30, 0, v30
	v_mul_f32_e32 v26, v26, v26
	v_mul_f32_e32 v31, v27, v27
	v_max_f32_e32 v27, 0, v32
	v_mul_f32_e32 v32, v28, v28
	v_max_f32_e32 v28, 0, v33
	v_max_f32_e32 v29, 0, v29
	v_pk_mul_f32 v[24:25], v[112:113], v[24:25]
	v_pk_mul_f32 v[22:23], v[110:111], v[22:23]
	v_pk_mul_f32 v[20:21], v[20:21], v[134:135] op_sel_hi:[1,0]
	v_pk_mul_f32 v[18:19], v[18:19], v[134:135] op_sel_hi:[1,0]
	v_cvt_f32_i32_e32 v17, v17
	v_cvt_f32_i32_e32 v16, v16
	v_lshl_add_u64 v[34:35], v[34:35], 0, v[132:133]
	v_mul_f32_e32 v30, v30, v30
	v_mul_f32_e32 v27, v27, v27
	v_mul_f32_e32 v28, v28, v28
	v_mul_f32_e32 v29, v29, v29
	v_cvt_pk_bf16_f32 v26, v30, v26
	v_pk_mul_f32 v[24:25], v[24:25], v[134:135] op_sel_hi:[1,0]
	v_pk_mul_f32 v[22:23], v[22:23], v[134:135] op_sel_hi:[1,0]
	v_max_f32_e32 v18, 0, v18
	v_max_f32_e32 v19, 0, v19
	v_max_f32_e32 v20, 0, v20
	v_cvt_f32_i32_e32 v3, v3
	v_cvt_f32_i32_e32 v5, v5
	v_cvt_f32_i32_e32 v4, v4
	v_cvt_f32_i32_e32 v2, v2
	v_cvt_pk_bf16_f32 v27, v27, v28
	v_cvt_pk_bf16_f32 v28, v36, v31
	v_cvt_pk_bf16_f32 v29, v32, v29
	global_store_dwordx4 v[34:35], v[26:29], off
	v_pk_mul_f32 v[10:11], v[122:123], v[10:11]
	v_cvt_f32_i32_e32 v7, v7
	v_mul_f32_e32 v26, v18, v18
	v_max_f32_e32 v18, 0, v23
	v_mul_f32_e32 v23, v19, v19
	v_max_f32_e32 v19, 0, v24
	v_mul_f32_e32 v24, v20, v20
	v_max_f32_e32 v20, 0, v25
	v_cvt_f32_i32_e32 v9, v9
	v_cvt_f32_i32_e32 v8, v8
	v_cvt_f32_i32_e32 v6, v6
	v_max_f32_e32 v22, 0, v22
	v_mul_f32_e32 v18, v18, v18
	v_mul_f32_e32 v19, v19, v19
	v_max_f32_e32 v21, 0, v21
	v_mul_f32_e32 v20, v20, v20
	v_pk_mul_f32 v[14:15], v[126:127], v[14:15]
	v_pk_mul_f32 v[12:13], v[124:125], v[12:13]
	v_pk_mul_f32 v[10:11], v[10:11], v[130:131] op_sel_hi:[1,0]
	v_mul_f32_e32 v22, v22, v22
	v_mul_f32_e32 v21, v21, v21
	v_cvt_pk_bf16_f32 v18, v22, v18
	v_cvt_pk_bf16_f32 v19, v19, v20
	v_cvt_pk_bf16_f32 v20, v26, v23
	v_pk_mul_f32 v[16:17], v[128:129], v[16:17]
	v_pk_mul_f32 v[14:15], v[14:15], v[130:131] op_sel_hi:[1,0]
	v_pk_mul_f32 v[12:13], v[12:13], v[130:131] op_sel_hi:[1,0]
	v_max_f32_e32 v10, 0, v10
	v_cvt_pk_bf16_f32 v21, v24, v21
	global_store_dwordx4 v[34:35], v[18:21], off offset:256
	v_pk_mul_f32 v[16:17], v[16:17], v[130:131] op_sel_hi:[1,0]
	v_max_f32_e32 v11, 0, v11
	v_mul_f32_e32 v20, v10, v10
	v_max_f32_e32 v10, 0, v15
	v_max_f32_e32 v12, 0, v12
	v_pk_mul_f32 v[4:5], v[108:109], v[4:5]
	v_pk_mul_f32 v[2:3], v[106:107], v[2:3]
	v_mad_i64_i32 v[18:19], s[38:39], v131, s55, v[162:163]
	v_max_f32_e32 v14, 0, v14
	v_mul_f32_e32 v10, v10, v10
	v_mul_f32_e32 v15, v11, v11
	v_max_f32_e32 v11, 0, v16
	v_mul_f32_e32 v16, v12, v12
	v_max_f32_e32 v12, 0, v17
	v_max_f32_e32 v13, 0, v13
	v_pk_mul_f32 v[8:9], v[112:113], v[8:9]
	v_pk_mul_f32 v[6:7], v[110:111], v[6:7]
	v_pk_mul_f32 v[4:5], v[4:5], v[130:131] op_sel_hi:[1,0]
	v_pk_mul_f32 v[2:3], v[2:3], v[130:131] op_sel_hi:[1,0]
	v_lshl_add_u64 v[18:19], v[18:19], 0, v[132:133]
	v_mul_f32_e32 v14, v14, v14
	v_mul_f32_e32 v11, v11, v11
	v_mul_f32_e32 v12, v12, v12
	v_mul_f32_e32 v13, v13, v13
	v_cvt_pk_bf16_f32 v10, v14, v10
	v_pk_mul_f32 v[8:9], v[8:9], v[130:131] op_sel_hi:[1,0]
	v_pk_mul_f32 v[6:7], v[6:7], v[130:131] op_sel_hi:[1,0]
	v_max_f32_e32 v2, 0, v2
	v_max_f32_e32 v3, 0, v3
	v_max_f32_e32 v4, 0, v4
	v_cvt_pk_bf16_f32 v11, v11, v12
	v_cvt_pk_bf16_f32 v12, v20, v15
	v_cvt_pk_bf16_f32 v13, v16, v13
	global_store_dwordx4 v[18:19], v[10:13], off
	v_max_f32_e32 v5, 0, v5
	v_max_f32_e32 v6, 0, v6
	v_mul_f32_e32 v10, v2, v2
	v_max_f32_e32 v2, 0, v7
	v_mul_f32_e32 v7, v3, v3
	v_max_f32_e32 v3, 0, v8
	v_mul_f32_e32 v8, v4, v4
	v_max_f32_e32 v4, 0, v9
	v_mul_f32_e32 v2, v2, v2
	v_mul_f32_e32 v3, v3, v3
	v_mul_f32_e32 v4, v4, v4
	v_mul_f32_e32 v5, v5, v5
	s_andn2_b64 vcc, exec, s[4:5]
	s_mov_b64 s[4:5], -1
	v_mul_f32_e32 v6, v6, v6
	v_cvt_pk_bf16_f32 v2, v6, v2
	v_cvt_pk_bf16_f32 v3, v3, v4
	v_cvt_pk_bf16_f32 v4, v10, v7
	v_cvt_pk_bf16_f32 v5, v8, v5
	global_store_dwordx4 v[18:19], v[2:5], off offset:256
	s_cbranch_vccnz .LBB0_1470
	s_andn2_b64 vcc, exec, s[18:19]
	s_cbranch_vccnz .LBB0_1469
	s_barrier
	s_branch .LBB0_1469
